# code placement: every MFMA segment of the five big GEMM K-loops at byte phase 4 mod 8 (single s_nop at the start of the preceding load segment where needed)
# speedup vs baseline: 1.0137x; 1.0095x over previous
; #define PG8_STAGE(bufoff, gbase, voff) do { _Pragma("unroll") for (int _i = 0; _i < 2; ++_i) \
;         __builtin_amdgcn_global_load_lds((const unsigned*)((const char*)(gbase) + (voff)[_i]), (PG8_LAS unsigned*)(lds + (bufoff) + ldsw + _i * 8192), 16, 0, 0); } while (0)
; #define PG8_LDA(dst, b, h) do { _Pragma("unroll") for (int m = 0; m < 4; ++m) _Pragma("unroll") for (int k = 0; k < 2; ++k) dst[m][k] = *(const PG8_LAS bf16x8*)(lds + PG8_SA(b, h) + aoff + m * 2048 + k * 1024); } while (0)
; #define PG8_LDB(dst, b, h) do { _Pragma("unroll") for (int n = 0; n < 2; ++n) _Pragma("unroll") for (int k = 0; k < 2; ++k) dst[n][k] = *(const PG8_LAS bf16x8*)(lds + PG8_SB(b, h) + boff + n * 2048 + k * 1024); } while (0)
; #define PG8_MMA(ai, bj, At, Bt) do { __builtin_amdgcn_s_setprio(1); _Pragma("unroll") for (int m = 0; m < 4; ++m) _Pragma("unroll") for (int n = 0; n < 2; ++n) _Pragma("unroll") for (int k = 0; k < 2; ++k) \
;         acc[ai][bj][m][n] = __builtin_amdgcn_mfma_f32_16x16x32_bf16(Bt[n][k], At[m][k], acc[ai][bj][m][n], 0, 0, 0); __builtin_amdgcn_s_setprio(0); } while (0)
; #define PG8_WAIT_V(n) asm volatile("s_waitcnt vmcnt(" #n ")" ::: "memory")
; #define PG8_WAIT_L(n) asm volatile("s_waitcnt lgkmcnt(" #n ")" ::: "memory")
; #define PG8_BAR __builtin_amdgcn_s_barrier()
; #define PG8_SCHED __builtin_amdgcn_sched_barrier(0)
; template <class Epi, class Sched, bool ALIGN_EPI = false, bool SP2 = false, bool AROWS128 = false>
; __device__ __forceinline__ void gemm_phase(PG8_LAS unsigned char* lds, const Gemm g, const Sched& S, const Epi& E) {
;     ...
;             PG8_LDB(B0, 0, 0); PG8_LDB(B1, 0, 1); PG8_SCHED; PG8_LDA(At, 0, 0); PG8_STAGE(PG8_SA(1, 1), a1 + hstepA, voffA);
;             PG8_WAIT_V(8); PG8_WAIT_L(0); PG8_BAR; PG8_MMA(0, 0, At, B0); PG8_MMA(0, 1, At, B1); PG8_BAR; PG8_SCHED;
;             PG8_LDA(At, 0, 1); PG8_STAGE(PG8_SB(0, 0), b2, voffB); PG8_STAGE(PG8_SB(0, 1), b2 + hstep, voffB); PG8_STAGE(PG8_SA(0, 0), a2, voffA);
.LBB0_119:
	ds_read_b128 v[148:151], v155
	ds_read_b128 v[160:163], v155 offset:1024
	ds_read_b128 v[164:167], v155 offset:2048
	ds_read_b128 v[168:171], v155 offset:3072
	ds_read_b128 v[172:175], v156
	ds_read_b128 v[176:179], v156 offset:1024
	ds_read_b128 v[180:183], v156 offset:2048
	ds_read_b128 v[184:187], v156 offset:3072
	s_add_u32 s50, s48, 0xfffc0080
	s_addc_u32 s51, s49, -1
	s_cmp_eq_u32 s93, 12
	s_cselect_b32 s59, s25, s51
	s_cselect_b32 s58, s76, s50
	s_cselect_b32 s51, s15, s92
	s_cselect_b32 s50, s77, s91
	v_lshl_add_u64 v[208:209], s[48:49], 0, v[138:139]
	s_add_i32 m0, s31, 0xc000
	ds_read_b128 v[188:191], v157
	ds_read_b128 v[192:195], v157 offset:1024
	ds_read_b128 v[196:199], v157 offset:2048
	ds_read_b128 v[200:203], v157 offset:3072
	ds_read_b128 v[204:207], v157 offset:4096
	ds_read_b128 v[212:215], v157 offset:5120
	ds_read_b128 v[216:219], v157 offset:6144
	ds_read_b128 v[220:223], v157 offset:7168
	global_load_lds_dwordx4 v[208:209], off
	v_lshl_add_u64 v[208:209], s[48:49], 0, v[140:141]
	s_add_i32 m0, s31, 0xe000
	s_nop 0
	global_load_lds_dwordx4 v[208:209], off
	s_waitcnt vmcnt(8)
	s_waitcnt lgkmcnt(0)
	s_barrier
	s_setprio 1
	s_waitcnt lgkmcnt(0)
	v_mfma_f32_16x16x32_bf16 v[124:127], v[148:151], v[188:191], v[124:127]
	v_mfma_f32_16x16x32_bf16 v[120:123], v[164:167], v[188:191], v[120:123]
	v_mfma_f32_16x16x32_bf16 v[112:115], v[148:151], v[196:199], v[112:115]
	v_mfma_f32_16x16x32_bf16 v[104:107], v[164:167], v[196:199], v[104:107]
	v_mfma_f32_16x16x32_bf16 v[96:99], v[148:151], v[204:207], v[96:99]
	v_mfma_f32_16x16x32_bf16 v[88:91], v[164:167], v[204:207], v[88:91]
	v_mfma_f32_16x16x32_bf16 v[80:83], v[148:151], v[216:219], v[80:83]
	v_mfma_f32_16x16x32_bf16 v[72:75], v[164:167], v[216:219], v[72:75]
	v_mfma_f32_16x16x32_bf16 v[124:127], v[160:163], v[192:195], v[124:127]
	v_mfma_f32_16x16x32_bf16 v[120:123], v[168:171], v[192:195], v[120:123]
	v_mfma_f32_16x16x32_bf16 v[112:115], v[160:163], v[200:203], v[112:115]
	v_mfma_f32_16x16x32_bf16 v[104:107], v[168:171], v[200:203], v[104:107]
	v_mfma_f32_16x16x32_bf16 v[96:99], v[160:163], v[212:215], v[96:99]
	v_mfma_f32_16x16x32_bf16 v[88:91], v[168:171], v[212:215], v[88:91]
	v_mfma_f32_16x16x32_bf16 v[80:83], v[160:163], v[220:223], v[80:83]
	v_mfma_f32_16x16x32_bf16 v[72:75], v[168:171], v[220:223], v[72:75]
	s_setprio 0
	s_setprio 1
	v_mfma_f32_16x16x32_bf16 v[116:119], v[172:175], v[188:191], v[116:119]
	v_mfma_f32_16x16x32_bf16 v[108:111], v[180:183], v[188:191], v[108:111]
	v_mfma_f32_16x16x32_bf16 v[100:103], v[172:175], v[196:199], v[100:103]
	v_mfma_f32_16x16x32_bf16 v[92:95], v[180:183], v[196:199], v[92:95]
	v_mfma_f32_16x16x32_bf16 v[84:87], v[172:175], v[204:207], v[84:87]
	v_mfma_f32_16x16x32_bf16 v[76:79], v[180:183], v[204:207], v[76:79]
	v_mfma_f32_16x16x32_bf16 v[68:71], v[172:175], v[216:219], v[68:71]
	v_mfma_f32_16x16x32_bf16 v[64:67], v[180:183], v[216:219], v[64:67]
	v_mfma_f32_16x16x32_bf16 v[116:119], v[176:179], v[192:195], v[116:119]
	v_mfma_f32_16x16x32_bf16 v[108:111], v[184:187], v[192:195], v[108:111]
	v_mfma_f32_16x16x32_bf16 v[100:103], v[176:179], v[200:203], v[100:103]
	v_mfma_f32_16x16x32_bf16 v[92:95], v[184:187], v[200:203], v[92:95]
	v_mfma_f32_16x16x32_bf16 v[84:87], v[176:179], v[212:215], v[84:87]
	v_mfma_f32_16x16x32_bf16 v[76:79], v[184:187], v[212:215], v[76:79]
	v_mfma_f32_16x16x32_bf16 v[68:71], v[176:179], v[220:223], v[68:71]
	v_mfma_f32_16x16x32_bf16 v[64:67], v[184:187], v[220:223], v[64:67]
	s_setprio 0
	s_barrier
	s_nop 0
	s_add_i32 s94, s87, s3
	v_lshl_add_u64 v[208:209], s[50:51], 0, v[134:135]
	s_mov_b32 m0, s94
	ds_read_b128 v[188:191], v157 offset:16384
	ds_read_b128 v[192:195], v157 offset:17408
	ds_read_b128 v[196:199], v157 offset:18432
	ds_read_b128 v[200:203], v157 offset:19456
	ds_read_b128 v[204:207], v157 offset:20480
	ds_read_b128 v[212:215], v157 offset:21504
	ds_read_b128 v[216:219], v157 offset:22528
	ds_read_b128 v[220:223], v157 offset:23552
	global_load_lds_dwordx4 v[208:209], off
	s_add_i32 m0, s94, 0x2000
	s_add_u32 s94, s50, 0x40000
	v_lshl_add_u64 v[224:225], s[50:51], 0, v[130:131]
	s_addc_u32 s95, s51, 0
	s_add_i32 s96, s88, s3
	global_load_lds_dwordx4 v[224:225], off
	v_lshl_add_u64 v[226:227], s[94:95], 0, v[134:135]
	s_mov_b32 m0, s96
	v_lshl_add_u64 v[228:229], s[58:59], 0, v[132:133]
	global_load_lds_dwordx4 v[226:227], off
	v_lshl_add_u64 v[226:227], s[94:95], 0, v[130:131]
	s_add_i32 m0, s96, 0x2000
	s_nop 0
	global_load_lds_dwordx4 v[226:227], off
	v_lshl_add_u64 v[226:227], s[58:59], 0, v[136:137]
	s_mov_b32 m0, s31
	s_nop 0
	global_load_lds_dwordx4 v[226:227], off
	s_mov_b32 m0, s64
	s_nop 0
	global_load_lds_dwordx4 v[228:229], off
	s_waitcnt vmcnt(8)
	s_waitcnt lgkmcnt(0)
	s_barrier
; #define PG8_STAGE(bufoff, gbase, voff) do { _Pragma("unroll") for (int _i = 0; _i < 2; ++_i) \
;         __builtin_amdgcn_global_load_lds((const unsigned*)((const char*)(gbase) + (voff)[_i]), (PG8_LAS unsigned*)(lds + (bufoff) + ldsw + _i * 8192), 16, 0, 0); } while (0)
; #define PG8_LDA(dst, b, h) do { _Pragma("unroll") for (int m = 0; m < 4; ++m) _Pragma("unroll") for (int k = 0; k < 2; ++k) dst[m][k] = *(const PG8_LAS bf16x8*)(lds + PG8_SA(b, h) + aoff + m * 2048 + k * 1024); } while (0)
; #define PG8_LDB(dst, b, h) do { _Pragma("unroll") for (int n = 0; n < 2; ++n) _Pragma("unroll") for (int k = 0; k < 2; ++k) dst[n][k] = *(const PG8_LAS bf16x8*)(lds + PG8_SB(b, h) + boff + n * 2048 + k * 1024); } while (0)
; #define PG8_MMA(ai, bj, At, Bt) do { __builtin_amdgcn_s_setprio(1); _Pragma("unroll") for (int m = 0; m < 4; ++m) _Pragma("unroll") for (int n = 0; n < 2; ++n) _Pragma("unroll") for (int k = 0; k < 2; ++k) \
;         acc[ai][bj][m][n] = __builtin_amdgcn_mfma_f32_16x16x32_bf16(Bt[n][k], At[m][k], acc[ai][bj][m][n], 0, 0, 0); __builtin_amdgcn_s_setprio(0); } while (0)
; #define PG8_WAIT_V(n) asm volatile("s_waitcnt vmcnt(" #n ")" ::: "memory")
; #define PG8_WAIT_L(n) asm volatile("s_waitcnt lgkmcnt(" #n ")" ::: "memory")
; #define PG8_BAR __builtin_amdgcn_s_barrier()
; #define PG8_SCHED __builtin_amdgcn_sched_barrier(0)
; template <class Epi, class Sched, bool ALIGN_EPI = false, bool SP2 = false, bool AROWS128 = false>
; __device__ __forceinline__ void gemm_phase(PG8_LAS unsigned char* lds, const Gemm g, const Sched& S, const Epi& E) {
;     ...
;             PG8_WAIT_V(8); PG8_WAIT_L(0); PG8_BAR; PG8_MMA(1, 0, At, B0); PG8_MMA(1, 1, At, B1); PG8_BAR; PG8_SCHED;
;             PG8_LDB(B0, 1, 0); PG8_LDB(B1, 1, 1); PG8_SCHED; PG8_LDA(At, 1, 0); PG8_STAGE(PG8_SA(0, 1), a2 + hstepA, voffA);
;             PG8_WAIT_V(8); PG8_WAIT_L(0); PG8_BAR; PG8_MMA(0, 0, At, B0); PG8_MMA(0, 1, At, B1); PG8_BAR; PG8_SCHED;
	s_setprio 1
	s_waitcnt lgkmcnt(0)
	v_mfma_f32_16x16x32_bf16 v[60:63], v[148:151], v[188:191], v[60:63]
	v_mfma_f32_16x16x32_bf16 v[56:59], v[164:167], v[188:191], v[56:59]
	v_mfma_f32_16x16x32_bf16 v[48:51], v[148:151], v[196:199], v[48:51]
	v_mfma_f32_16x16x32_bf16 v[40:43], v[164:167], v[196:199], v[40:43]
	v_mfma_f32_16x16x32_bf16 v[32:35], v[148:151], v[204:207], v[32:35]
	v_mfma_f32_16x16x32_bf16 v[24:27], v[164:167], v[204:207], v[24:27]
	v_mfma_f32_16x16x32_bf16 v[16:19], v[148:151], v[216:219], v[16:19]
	v_mfma_f32_16x16x32_bf16 v[8:11], v[164:167], v[216:219], v[8:11]
	v_mfma_f32_16x16x32_bf16 v[60:63], v[160:163], v[192:195], v[60:63]
	v_mfma_f32_16x16x32_bf16 v[56:59], v[168:171], v[192:195], v[56:59]
	v_mfma_f32_16x16x32_bf16 v[48:51], v[160:163], v[200:203], v[48:51]
	v_mfma_f32_16x16x32_bf16 v[40:43], v[168:171], v[200:203], v[40:43]
	v_mfma_f32_16x16x32_bf16 v[32:35], v[160:163], v[212:215], v[32:35]
	v_mfma_f32_16x16x32_bf16 v[24:27], v[168:171], v[212:215], v[24:27]
	v_mfma_f32_16x16x32_bf16 v[16:19], v[160:163], v[220:223], v[16:19]
	v_mfma_f32_16x16x32_bf16 v[8:11], v[168:171], v[220:223], v[8:11]
	s_setprio 0
	s_setprio 1
	v_mfma_f32_16x16x32_bf16 v[52:55], v[172:175], v[188:191], v[52:55]
	v_mfma_f32_16x16x32_bf16 v[44:47], v[180:183], v[188:191], v[44:47]
	v_mfma_f32_16x16x32_bf16 v[36:39], v[172:175], v[196:199], v[36:39]
	v_mfma_f32_16x16x32_bf16 v[28:31], v[180:183], v[196:199], v[28:31]
	v_mfma_f32_16x16x32_bf16 v[20:23], v[172:175], v[204:207], v[20:23]
	v_mfma_f32_16x16x32_bf16 v[12:15], v[180:183], v[204:207], v[12:15]
	v_mfma_f32_16x16x32_bf16 v[4:7], v[172:175], v[216:219], v[4:7]
	v_mfma_f32_16x16x32_bf16 v[0:3], v[180:183], v[216:219], v[0:3]
	v_mfma_f32_16x16x32_bf16 v[52:55], v[176:179], v[192:195], v[52:55]
	v_mfma_f32_16x16x32_bf16 v[44:47], v[184:187], v[192:195], v[44:47]
	v_mfma_f32_16x16x32_bf16 v[36:39], v[176:179], v[200:203], v[36:39]
	v_mfma_f32_16x16x32_bf16 v[28:31], v[184:187], v[200:203], v[28:31]
	v_mfma_f32_16x16x32_bf16 v[20:23], v[176:179], v[212:215], v[20:23]
	v_mfma_f32_16x16x32_bf16 v[12:15], v[184:187], v[212:215], v[12:15]
	v_mfma_f32_16x16x32_bf16 v[4:7], v[176:179], v[220:223], v[4:7]
	v_mfma_f32_16x16x32_bf16 v[0:3], v[184:187], v[220:223], v[0:3]
	s_setprio 0
	s_barrier
	s_nop 0
	s_add_i32 s94, 0, 0x18000
	v_add_u32_e32 v146, s94, v153
	s_add_i32 s95, 0, 0x1c000
	ds_read_b128 v[148:151], v146
	ds_read_b128 v[160:163], v146 offset:1024
	ds_read_b128 v[164:167], v146 offset:2048
	ds_read_b128 v[168:171], v146 offset:3072
	v_add_u32_e32 v146, s95, v153
	ds_read_b128 v[172:175], v146
	ds_read_b128 v[176:179], v146 offset:1024
	ds_read_b128 v[180:183], v146 offset:2048
	ds_read_b128 v[184:187], v146 offset:3072
	s_add_u32 s58, s58, 0x40000
	s_addc_u32 s59, s59, 0
	s_mov_b32 m0, s65
	v_lshl_add_u64 v[230:231], s[58:59], 0, v[136:137]
	ds_read_b128 v[188:191], v157 offset:32768
	ds_read_b128 v[192:195], v157 offset:33792
	ds_read_b128 v[196:199], v157 offset:34816
	ds_read_b128 v[200:203], v157 offset:35840
	ds_read_b128 v[204:207], v157 offset:36864
	ds_read_b128 v[212:215], v157 offset:37888
	ds_read_b128 v[216:219], v157 offset:38912
	ds_read_b128 v[220:223], v157 offset:39936
	global_load_lds_dwordx4 v[230:231], off
	v_lshl_add_u64 v[230:231], s[58:59], 0, v[132:133]
	s_mov_b32 m0, s72
	s_nop 0
	global_load_lds_dwordx4 v[230:231], off
	s_waitcnt vmcnt(8)
	s_waitcnt lgkmcnt(0)
	s_barrier
	s_setprio 1
	s_waitcnt lgkmcnt(0)
	v_mfma_f32_16x16x32_bf16 v[124:127], v[148:151], v[188:191], v[124:127]
	v_mfma_f32_16x16x32_bf16 v[120:123], v[164:167], v[188:191], v[120:123]
	v_mfma_f32_16x16x32_bf16 v[112:115], v[148:151], v[196:199], v[112:115]
	v_mfma_f32_16x16x32_bf16 v[104:107], v[164:167], v[196:199], v[104:107]
	v_mfma_f32_16x16x32_bf16 v[96:99], v[148:151], v[204:207], v[96:99]
	v_mfma_f32_16x16x32_bf16 v[88:91], v[164:167], v[204:207], v[88:91]
	v_mfma_f32_16x16x32_bf16 v[80:83], v[148:151], v[216:219], v[80:83]
	v_mfma_f32_16x16x32_bf16 v[72:75], v[164:167], v[216:219], v[72:75]
	v_mfma_f32_16x16x32_bf16 v[124:127], v[160:163], v[192:195], v[124:127]
	v_mfma_f32_16x16x32_bf16 v[120:123], v[168:171], v[192:195], v[120:123]
	v_mfma_f32_16x16x32_bf16 v[112:115], v[160:163], v[200:203], v[112:115]
	v_mfma_f32_16x16x32_bf16 v[104:107], v[168:171], v[200:203], v[104:107]
	v_mfma_f32_16x16x32_bf16 v[96:99], v[160:163], v[212:215], v[96:99]
	v_mfma_f32_16x16x32_bf16 v[88:91], v[168:171], v[212:215], v[88:91]
	v_mfma_f32_16x16x32_bf16 v[80:83], v[160:163], v[220:223], v[80:83]
	v_mfma_f32_16x16x32_bf16 v[72:75], v[168:171], v[220:223], v[72:75]
	s_setprio 0
	s_setprio 1
	v_mfma_f32_16x16x32_bf16 v[116:119], v[172:175], v[188:191], v[116:119]
	v_mfma_f32_16x16x32_bf16 v[108:111], v[180:183], v[188:191], v[108:111]
	v_mfma_f32_16x16x32_bf16 v[100:103], v[172:175], v[196:199], v[100:103]
	v_mfma_f32_16x16x32_bf16 v[92:95], v[180:183], v[196:199], v[92:95]
	v_mfma_f32_16x16x32_bf16 v[84:87], v[172:175], v[204:207], v[84:87]
	v_mfma_f32_16x16x32_bf16 v[76:79], v[180:183], v[204:207], v[76:79]
	v_mfma_f32_16x16x32_bf16 v[68:71], v[172:175], v[216:219], v[68:71]
	v_mfma_f32_16x16x32_bf16 v[64:67], v[180:183], v[216:219], v[64:67]
	v_mfma_f32_16x16x32_bf16 v[116:119], v[176:179], v[192:195], v[116:119]
	v_mfma_f32_16x16x32_bf16 v[108:111], v[184:187], v[192:195], v[108:111]
	v_mfma_f32_16x16x32_bf16 v[100:103], v[176:179], v[200:203], v[100:103]
	v_mfma_f32_16x16x32_bf16 v[92:95], v[184:187], v[200:203], v[92:95]
	v_mfma_f32_16x16x32_bf16 v[84:87], v[176:179], v[212:215], v[84:87]
	v_mfma_f32_16x16x32_bf16 v[76:79], v[184:187], v[212:215], v[76:79]
	v_mfma_f32_16x16x32_bf16 v[68:71], v[176:179], v[220:223], v[68:71]
	v_mfma_f32_16x16x32_bf16 v[64:67], v[184:187], v[220:223], v[64:67]
	s_setprio 0
	s_barrier
; #define PG8_STAGE(bufoff, gbase, voff) do { _Pragma("unroll") for (int _i = 0; _i < 2; ++_i) \
;         __builtin_amdgcn_global_load_lds((const unsigned*)((const char*)(gbase) + (voff)[_i]), (PG8_LAS unsigned*)(lds + (bufoff) + ldsw + _i * 8192), 16, 0, 0); } while (0)
; #define PG8_LDA(dst, b, h) do { _Pragma("unroll") for (int m = 0; m < 4; ++m) _Pragma("unroll") for (int k = 0; k < 2; ++k) dst[m][k] = *(const PG8_LAS bf16x8*)(lds + PG8_SA(b, h) + aoff + m * 2048 + k * 1024); } while (0)
; #define PG8_MMA(ai, bj, At, Bt) do { __builtin_amdgcn_s_setprio(1); _Pragma("unroll") for (int m = 0; m < 4; ++m) _Pragma("unroll") for (int n = 0; n < 2; ++n) _Pragma("unroll") for (int k = 0; k < 2; ++k) \
;         acc[ai][bj][m][n] = __builtin_amdgcn_mfma_f32_16x16x32_bf16(Bt[n][k], At[m][k], acc[ai][bj][m][n], 0, 0, 0); __builtin_amdgcn_s_setprio(0); } while (0)
; #define PG8_WAIT_V(n) asm volatile("s_waitcnt vmcnt(" #n ")" ::: "memory")
; #define PG8_WAIT_L(n) asm volatile("s_waitcnt lgkmcnt(" #n ")" ::: "memory")
; #define PG8_BAR __builtin_amdgcn_s_barrier()
; #define PG8_SCHED __builtin_amdgcn_sched_barrier(0)
; template <class Epi, class Sched, bool ALIGN_EPI = false, bool SP2 = false, bool AROWS128 = false>
; __device__ __forceinline__ void gemm_phase(PG8_LAS unsigned char* lds, const Gemm g, const Sched& S, const Epi& E) {
;     ...
;         for (int t = 0; t < nt; t += 2) {
;     ...
;             PG8_LDA(At, 1, 1); PG8_STAGE(PG8_SB(1, 0), b3, voffB); PG8_STAGE(PG8_SB(1, 1), b3 + hstep, voffB); PG8_STAGE(PG8_SA(1, 0), a3, voffA);
;             PG8_WAIT_V(8); PG8_WAIT_L(0); PG8_BAR; PG8_MMA(1, 0, At, B0); PG8_MMA(1, 1, At, B1); PG8_BAR; PG8_SCHED;
	s_add_i32 s58, s94, s3
	v_lshl_add_u64 v[208:209], v[208:209], 0, s[6:7]
	s_mov_b32 m0, s58
	ds_read_b128 v[188:191], v157 offset:49152
	ds_read_b128 v[192:195], v157 offset:50176
	ds_read_b128 v[196:199], v157 offset:51200
	ds_read_b128 v[200:203], v157 offset:52224
	ds_read_b128 v[204:207], v157 offset:53248
	ds_read_b128 v[212:215], v157 offset:54272
	ds_read_b128 v[216:219], v157 offset:55296
	ds_read_b128 v[220:223], v157 offset:56320
	global_load_lds_dwordx4 v[208:209], off
	s_add_i32 m0, s58, 0x2000
	s_add_u32 s50, s50, 0x40080
	v_lshl_add_u64 v[208:209], v[224:225], 0, s[6:7]
	s_addc_u32 s51, s51, 0
	s_add_i32 s58, s95, s3
	global_load_lds_dwordx4 v[208:209], off
	v_lshl_add_u64 v[208:209], s[50:51], 0, v[134:135]
	s_mov_b32 m0, s58
	s_nop 0
	global_load_lds_dwordx4 v[208:209], off
	v_lshl_add_u64 v[208:209], s[50:51], 0, v[130:131]
	s_add_i32 m0, s58, 0x2000
	s_nop 0
	global_load_lds_dwordx4 v[208:209], off
	v_lshl_add_u64 v[208:209], v[226:227], 0, s[6:7]
	s_mov_b32 m0, s81
	s_nop 0
	global_load_lds_dwordx4 v[208:209], off
	v_lshl_add_u64 v[208:209], v[228:229], 0, s[6:7]
	s_mov_b32 m0, s84
	s_nop 0
	global_load_lds_dwordx4 v[208:209], off
	s_waitcnt vmcnt(8)
	s_waitcnt lgkmcnt(0)
	s_barrier
	s_setprio 1
	s_waitcnt lgkmcnt(0)
	v_mfma_f32_16x16x32_bf16 v[60:63], v[148:151], v[188:191], v[60:63]
	v_mfma_f32_16x16x32_bf16 v[56:59], v[164:167], v[188:191], v[56:59]
	v_mfma_f32_16x16x32_bf16 v[48:51], v[148:151], v[196:199], v[48:51]
	v_mfma_f32_16x16x32_bf16 v[40:43], v[164:167], v[196:199], v[40:43]
	v_mfma_f32_16x16x32_bf16 v[32:35], v[148:151], v[204:207], v[32:35]
	v_mfma_f32_16x16x32_bf16 v[24:27], v[164:167], v[204:207], v[24:27]
	v_mfma_f32_16x16x32_bf16 v[16:19], v[148:151], v[216:219], v[16:19]
	v_mfma_f32_16x16x32_bf16 v[8:11], v[164:167], v[216:219], v[8:11]
	v_mfma_f32_16x16x32_bf16 v[60:63], v[160:163], v[192:195], v[60:63]
	v_mfma_f32_16x16x32_bf16 v[56:59], v[168:171], v[192:195], v[56:59]
	v_mfma_f32_16x16x32_bf16 v[48:51], v[160:163], v[200:203], v[48:51]
	v_mfma_f32_16x16x32_bf16 v[40:43], v[168:171], v[200:203], v[40:43]
	v_mfma_f32_16x16x32_bf16 v[32:35], v[160:163], v[212:215], v[32:35]
	v_mfma_f32_16x16x32_bf16 v[24:27], v[168:171], v[212:215], v[24:27]
	v_mfma_f32_16x16x32_bf16 v[16:19], v[160:163], v[220:223], v[16:19]
	v_mfma_f32_16x16x32_bf16 v[8:11], v[168:171], v[220:223], v[8:11]
	s_setprio 0
	s_setprio 1
	v_mfma_f32_16x16x32_bf16 v[52:55], v[172:175], v[188:191], v[52:55]
	v_mfma_f32_16x16x32_bf16 v[44:47], v[180:183], v[188:191], v[44:47]
	v_mfma_f32_16x16x32_bf16 v[36:39], v[172:175], v[196:199], v[36:39]
	v_mfma_f32_16x16x32_bf16 v[28:31], v[180:183], v[196:199], v[28:31]
	v_mfma_f32_16x16x32_bf16 v[20:23], v[172:175], v[204:207], v[20:23]
	v_mfma_f32_16x16x32_bf16 v[12:15], v[180:183], v[204:207], v[12:15]
	v_mfma_f32_16x16x32_bf16 v[4:7], v[172:175], v[216:219], v[4:7]
	v_mfma_f32_16x16x32_bf16 v[0:3], v[180:183], v[216:219], v[0:3]
	v_mfma_f32_16x16x32_bf16 v[52:55], v[176:179], v[192:195], v[52:55]
	v_mfma_f32_16x16x32_bf16 v[44:47], v[184:187], v[192:195], v[44:47]
	v_mfma_f32_16x16x32_bf16 v[36:39], v[176:179], v[200:203], v[36:39]
	v_mfma_f32_16x16x32_bf16 v[28:31], v[184:187], v[200:203], v[28:31]
	v_mfma_f32_16x16x32_bf16 v[20:23], v[176:179], v[212:215], v[20:23]
	v_mfma_f32_16x16x32_bf16 v[12:15], v[184:187], v[212:215], v[12:15]
	v_mfma_f32_16x16x32_bf16 v[4:7], v[176:179], v[220:223], v[4:7]
	v_mfma_f32_16x16x32_bf16 v[0:3], v[184:187], v[220:223], v[0:3]
	s_setprio 0
	s_barrier
	s_add_i32 s93, s93, 2
	s_add_u32 s48, s48, 0x100
	s_addc_u32 s49, s49, 0
	s_add_u32 s91, s91, 0x100
	s_addc_u32 s92, s92, 0
	s_cmp_gt_u32 s93, 13
	s_cbranch_scc0 .LBB0_119
	s_and_b64 vcc, exec, s[10:11]
	s_cbranch_vccz .LBB0_122
	s_barrier

; #define PG8_STAGE(bufoff, gbase, voff) do { _Pragma("unroll") for (int _i = 0; _i < 2; ++_i) \
;         __builtin_amdgcn_global_load_lds((const unsigned*)((const char*)(gbase) + (voff)[_i]), (PG8_LAS unsigned*)(lds + (bufoff) + ldsw + _i * 8192), 16, 0, 0); } while (0)
; #define PG8_LDA(dst, b, h) do { _Pragma("unroll") for (int m = 0; m < 4; ++m) _Pragma("unroll") for (int k = 0; k < 2; ++k) dst[m][k] = *(const PG8_LAS bf16x8*)(lds + PG8_SA(b, h) + aoff + m * 2048 + k * 1024); } while (0)
; #define PG8_LDB(dst, b, h) do { _Pragma("unroll") for (int n = 0; n < 2; ++n) _Pragma("unroll") for (int k = 0; k < 2; ++k) dst[n][k] = *(const PG8_LAS bf16x8*)(lds + PG8_SB(b, h) + boff + n * 2048 + k * 1024); } while (0)
; #define PG8_MMA(ai, bj, At, Bt) do { __builtin_amdgcn_s_setprio(1); _Pragma("unroll") for (int m = 0; m < 4; ++m) _Pragma("unroll") for (int n = 0; n < 2; ++n) _Pragma("unroll") for (int k = 0; k < 2; ++k) \
;         acc[ai][bj][m][n] = __builtin_amdgcn_mfma_f32_16x16x32_bf16(Bt[n][k], At[m][k], acc[ai][bj][m][n], 0, 0, 0); __builtin_amdgcn_s_setprio(0); } while (0)
; #define PG8_WAIT_V(n) asm volatile("s_waitcnt vmcnt(" #n ")" ::: "memory")
; #define PG8_WAIT_L(n) asm volatile("s_waitcnt lgkmcnt(" #n ")" ::: "memory")
; #define PG8_BAR __builtin_amdgcn_s_barrier()
; #define PG8_SCHED __builtin_amdgcn_sched_barrier(0)
; template <class Epi, class Sched, bool ALIGN_EPI = false, bool SP2 = false, bool AROWS128 = false>
; __device__ __forceinline__ void gemm_phase(PG8_LAS unsigned char* lds, const Gemm g, const Sched& S, const Epi& E) {
;     ...
;             PG8_LDB(B0, 0, 0); PG8_LDB(B1, 0, 1); PG8_SCHED; PG8_LDA(At, 0, 0); PG8_STAGE(PG8_SA(1, 1), a1 + hstepA, voffA);
;             PG8_WAIT_V(8); PG8_WAIT_L(0); PG8_BAR; PG8_MMA(0, 0, At, B0); PG8_MMA(0, 1, At, B1); PG8_BAR; PG8_SCHED;
;             PG8_LDA(At, 0, 1); PG8_STAGE(PG8_SB(0, 0), b2, voffB); PG8_STAGE(PG8_SB(0, 1), b2 + hstep, voffB); PG8_STAGE(PG8_SA(0, 0), a2, voffA);
.LBB0_489:
	ds_read_b128 v[152:155], v149
	ds_read_b128 v[156:159], v149 offset:1024
	ds_read_b128 v[160:163], v149 offset:2048
	ds_read_b128 v[164:167], v149 offset:3072
	ds_read_b128 v[168:171], v150
	ds_read_b128 v[172:175], v150 offset:1024
	ds_read_b128 v[176:179], v150 offset:2048
	ds_read_b128 v[180:183], v150 offset:3072
	s_add_u32 s28, s26, 0xfffc0080
	s_addc_u32 s29, s27, -1
	s_cmp_eq_u32 s84, 12
	s_cselect_b32 s31, s15, s29
	s_cselect_b32 s30, s76, s28
	s_cselect_b32 s29, s13, s83
	s_cselect_b32 s28, s77, s82
	v_lshl_add_u64 v[144:145], s[26:27], 0, v[136:137]
	s_add_i32 m0, s25, 0xc000
	ds_read_b128 v[184:187], v151
	ds_read_b128 v[188:191], v151 offset:1024
	ds_read_b128 v[192:195], v151 offset:2048
	ds_read_b128 v[196:199], v151 offset:3072
	ds_read_b128 v[200:203], v151 offset:4096
	ds_read_b128 v[204:207], v151 offset:5120
	ds_read_b128 v[212:215], v151 offset:6144
	ds_read_b128 v[216:219], v151 offset:7168
	global_load_lds_dwordx4 v[144:145], off
	v_lshl_add_u64 v[144:145], s[26:27], 0, v[138:139]
	s_add_i32 m0, s25, 0xe000
	s_nop 0
	global_load_lds_dwordx4 v[144:145], off
	s_waitcnt vmcnt(8)
	s_waitcnt lgkmcnt(0)
	s_barrier
	s_setprio 1
	s_waitcnt lgkmcnt(0)
	v_mfma_f32_16x16x32_bf16 v[124:127], v[152:155], v[184:187], v[124:127]
	v_mfma_f32_16x16x32_bf16 v[120:123], v[160:163], v[184:187], v[120:123]
	v_mfma_f32_16x16x32_bf16 v[116:119], v[152:155], v[192:195], v[116:119]
	v_mfma_f32_16x16x32_bf16 v[108:111], v[160:163], v[192:195], v[108:111]
	v_mfma_f32_16x16x32_bf16 v[100:103], v[152:155], v[200:203], v[100:103]
	v_mfma_f32_16x16x32_bf16 v[92:95], v[160:163], v[200:203], v[92:95]
	v_mfma_f32_16x16x32_bf16 v[84:87], v[152:155], v[212:215], v[84:87]
	v_mfma_f32_16x16x32_bf16 v[76:79], v[160:163], v[212:215], v[76:79]
	v_mfma_f32_16x16x32_bf16 v[124:127], v[156:159], v[188:191], v[124:127]
	v_mfma_f32_16x16x32_bf16 v[120:123], v[164:167], v[188:191], v[120:123]
	v_mfma_f32_16x16x32_bf16 v[116:119], v[156:159], v[196:199], v[116:119]
	v_mfma_f32_16x16x32_bf16 v[108:111], v[164:167], v[196:199], v[108:111]
	v_mfma_f32_16x16x32_bf16 v[100:103], v[156:159], v[204:207], v[100:103]
	v_mfma_f32_16x16x32_bf16 v[92:95], v[164:167], v[204:207], v[92:95]
	v_mfma_f32_16x16x32_bf16 v[84:87], v[156:159], v[216:219], v[84:87]
	v_mfma_f32_16x16x32_bf16 v[76:79], v[164:167], v[216:219], v[76:79]
	s_setprio 0
	s_setprio 1
	v_mfma_f32_16x16x32_bf16 v[112:115], v[168:171], v[184:187], v[112:115]
	v_mfma_f32_16x16x32_bf16 v[104:107], v[176:179], v[184:187], v[104:107]
	v_mfma_f32_16x16x32_bf16 v[96:99], v[168:171], v[192:195], v[96:99]
	v_mfma_f32_16x16x32_bf16 v[88:91], v[176:179], v[192:195], v[88:91]
	v_mfma_f32_16x16x32_bf16 v[80:83], v[168:171], v[200:203], v[80:83]
	v_mfma_f32_16x16x32_bf16 v[72:75], v[176:179], v[200:203], v[72:75]
	v_mfma_f32_16x16x32_bf16 v[68:71], v[168:171], v[212:215], v[68:71]
	v_mfma_f32_16x16x32_bf16 v[64:67], v[176:179], v[212:215], v[64:67]
	v_mfma_f32_16x16x32_bf16 v[112:115], v[172:175], v[188:191], v[112:115]
	v_mfma_f32_16x16x32_bf16 v[104:107], v[180:183], v[188:191], v[104:107]
	v_mfma_f32_16x16x32_bf16 v[96:99], v[172:175], v[196:199], v[96:99]
	v_mfma_f32_16x16x32_bf16 v[88:91], v[180:183], v[196:199], v[88:91]
	v_mfma_f32_16x16x32_bf16 v[80:83], v[172:175], v[204:207], v[80:83]
	v_mfma_f32_16x16x32_bf16 v[72:75], v[180:183], v[204:207], v[72:75]
	v_mfma_f32_16x16x32_bf16 v[68:71], v[172:175], v[216:219], v[68:71]
	v_mfma_f32_16x16x32_bf16 v[64:67], v[180:183], v[216:219], v[64:67]
	s_setprio 0
	s_barrier
	s_nop 0
	s_add_i32 s85, s72, s3
	v_lshl_add_u64 v[144:145], s[28:29], 0, v[132:133]
	s_mov_b32 m0, s85
	ds_read_b128 v[184:187], v151 offset:16384
	ds_read_b128 v[188:191], v151 offset:17408
	ds_read_b128 v[192:195], v151 offset:18432
	ds_read_b128 v[196:199], v151 offset:19456
	ds_read_b128 v[200:203], v151 offset:20480
	ds_read_b128 v[204:207], v151 offset:21504
	ds_read_b128 v[212:215], v151 offset:22528
	ds_read_b128 v[216:219], v151 offset:23552
	global_load_lds_dwordx4 v[144:145], off
	s_add_i32 m0, s85, 0x2000
	s_add_u32 s86, s28, 0x40000
	v_lshl_add_u64 v[208:209], s[28:29], 0, v[128:129]
	s_addc_u32 s87, s29, 0
	s_add_i32 s85, s73, s3
	global_load_lds_dwordx4 v[208:209], off
	v_lshl_add_u64 v[220:221], s[86:87], 0, v[132:133]
	s_mov_b32 m0, s85
	v_lshl_add_u64 v[222:223], s[30:31], 0, v[130:131]
	global_load_lds_dwordx4 v[220:221], off
	v_lshl_add_u64 v[220:221], s[86:87], 0, v[128:129]
	s_add_i32 m0, s85, 0x2000
	s_nop 0
	global_load_lds_dwordx4 v[220:221], off
	v_lshl_add_u64 v[220:221], s[30:31], 0, v[134:135]
	s_mov_b32 m0, s25
	s_nop 0
	global_load_lds_dwordx4 v[220:221], off
	s_mov_b32 m0, s50
	s_nop 0
	global_load_lds_dwordx4 v[222:223], off
	s_waitcnt vmcnt(8)
	s_waitcnt lgkmcnt(0)
	s_barrier
; #define PG8_STAGE(bufoff, gbase, voff) do { _Pragma("unroll") for (int _i = 0; _i < 2; ++_i) \
;         __builtin_amdgcn_global_load_lds((const unsigned*)((const char*)(gbase) + (voff)[_i]), (PG8_LAS unsigned*)(lds + (bufoff) + ldsw + _i * 8192), 16, 0, 0); } while (0)
; #define PG8_LDA(dst, b, h) do { _Pragma("unroll") for (int m = 0; m < 4; ++m) _Pragma("unroll") for (int k = 0; k < 2; ++k) dst[m][k] = *(const PG8_LAS bf16x8*)(lds + PG8_SA(b, h) + aoff + m * 2048 + k * 1024); } while (0)
; #define PG8_LDB(dst, b, h) do { _Pragma("unroll") for (int n = 0; n < 2; ++n) _Pragma("unroll") for (int k = 0; k < 2; ++k) dst[n][k] = *(const PG8_LAS bf16x8*)(lds + PG8_SB(b, h) + boff + n * 2048 + k * 1024); } while (0)
; #define PG8_MMA(ai, bj, At, Bt) do { __builtin_amdgcn_s_setprio(1); _Pragma("unroll") for (int m = 0; m < 4; ++m) _Pragma("unroll") for (int n = 0; n < 2; ++n) _Pragma("unroll") for (int k = 0; k < 2; ++k) \
;         acc[ai][bj][m][n] = __builtin_amdgcn_mfma_f32_16x16x32_bf16(Bt[n][k], At[m][k], acc[ai][bj][m][n], 0, 0, 0); __builtin_amdgcn_s_setprio(0); } while (0)
; #define PG8_WAIT_V(n) asm volatile("s_waitcnt vmcnt(" #n ")" ::: "memory")
; #define PG8_WAIT_L(n) asm volatile("s_waitcnt lgkmcnt(" #n ")" ::: "memory")
; #define PG8_BAR __builtin_amdgcn_s_barrier()
; #define PG8_SCHED __builtin_amdgcn_sched_barrier(0)
; template <class Epi, class Sched, bool ALIGN_EPI = false, bool SP2 = false, bool AROWS128 = false>
; __device__ __forceinline__ void gemm_phase(PG8_LAS unsigned char* lds, const Gemm g, const Sched& S, const Epi& E) {
;     ...
;             PG8_WAIT_V(8); PG8_WAIT_L(0); PG8_BAR; PG8_MMA(1, 0, At, B0); PG8_MMA(1, 1, At, B1); PG8_BAR; PG8_SCHED;
;             PG8_LDB(B0, 1, 0); PG8_LDB(B1, 1, 1); PG8_SCHED; PG8_LDA(At, 1, 0); PG8_STAGE(PG8_SA(0, 1), a2 + hstepA, voffA);
;             PG8_WAIT_V(8); PG8_WAIT_L(0); PG8_BAR; PG8_MMA(0, 0, At, B0); PG8_MMA(0, 1, At, B1); PG8_BAR; PG8_SCHED;
	s_setprio 1
	s_waitcnt lgkmcnt(0)
	v_mfma_f32_16x16x32_bf16 v[60:63], v[152:155], v[184:187], v[60:63]
	v_mfma_f32_16x16x32_bf16 v[56:59], v[160:163], v[184:187], v[56:59]
	v_mfma_f32_16x16x32_bf16 v[52:55], v[152:155], v[192:195], v[52:55]
	v_mfma_f32_16x16x32_bf16 v[44:47], v[160:163], v[192:195], v[44:47]
	v_mfma_f32_16x16x32_bf16 v[36:39], v[152:155], v[200:203], v[36:39]
	v_mfma_f32_16x16x32_bf16 v[28:31], v[160:163], v[200:203], v[28:31]
	v_mfma_f32_16x16x32_bf16 v[20:23], v[152:155], v[212:215], v[20:23]
	v_mfma_f32_16x16x32_bf16 v[12:15], v[160:163], v[212:215], v[12:15]
	v_mfma_f32_16x16x32_bf16 v[60:63], v[156:159], v[188:191], v[60:63]
	v_mfma_f32_16x16x32_bf16 v[56:59], v[164:167], v[188:191], v[56:59]
	v_mfma_f32_16x16x32_bf16 v[52:55], v[156:159], v[196:199], v[52:55]
	v_mfma_f32_16x16x32_bf16 v[44:47], v[164:167], v[196:199], v[44:47]
	v_mfma_f32_16x16x32_bf16 v[36:39], v[156:159], v[204:207], v[36:39]
	v_mfma_f32_16x16x32_bf16 v[28:31], v[164:167], v[204:207], v[28:31]
	v_mfma_f32_16x16x32_bf16 v[20:23], v[156:159], v[216:219], v[20:23]
	v_mfma_f32_16x16x32_bf16 v[12:15], v[164:167], v[216:219], v[12:15]
	s_setprio 0
	s_setprio 1
	v_mfma_f32_16x16x32_bf16 v[48:51], v[168:171], v[184:187], v[48:51]
	v_mfma_f32_16x16x32_bf16 v[40:43], v[176:179], v[184:187], v[40:43]
	v_mfma_f32_16x16x32_bf16 v[32:35], v[168:171], v[192:195], v[32:35]
	v_mfma_f32_16x16x32_bf16 v[24:27], v[176:179], v[192:195], v[24:27]
	v_mfma_f32_16x16x32_bf16 v[16:19], v[168:171], v[200:203], v[16:19]
	v_mfma_f32_16x16x32_bf16 v[8:11], v[176:179], v[200:203], v[8:11]
	v_mfma_f32_16x16x32_bf16 v[4:7], v[168:171], v[212:215], v[4:7]
	v_mfma_f32_16x16x32_bf16 v[0:3], v[176:179], v[212:215], v[0:3]
	v_mfma_f32_16x16x32_bf16 v[48:51], v[172:175], v[188:191], v[48:51]
	v_mfma_f32_16x16x32_bf16 v[40:43], v[180:183], v[188:191], v[40:43]
	v_mfma_f32_16x16x32_bf16 v[32:35], v[172:175], v[196:199], v[32:35]
	v_mfma_f32_16x16x32_bf16 v[24:27], v[180:183], v[196:199], v[24:27]
	v_mfma_f32_16x16x32_bf16 v[16:19], v[172:175], v[204:207], v[16:19]
	v_mfma_f32_16x16x32_bf16 v[8:11], v[180:183], v[204:207], v[8:11]
	v_mfma_f32_16x16x32_bf16 v[4:7], v[172:175], v[216:219], v[4:7]
	v_mfma_f32_16x16x32_bf16 v[0:3], v[180:183], v[216:219], v[0:3]
	s_setprio 0
	s_barrier
	s_nop 0
	s_add_i32 s85, 0, 0x18000
	s_add_i32 s86, 0, 0x1c000
	v_add_u32_e32 v164, s85, v147
	v_add_u32_e32 v180, s86, v147
	ds_read_b128 v[152:155], v164
	ds_read_b128 v[156:159], v164 offset:1024
	ds_read_b128 v[160:163], v164 offset:2048
	ds_read_b128 v[164:167], v164 offset:3072
	ds_read_b128 v[168:171], v180
	ds_read_b128 v[172:175], v180 offset:1024
	ds_read_b128 v[176:179], v180 offset:2048
	ds_read_b128 v[180:183], v180 offset:3072
	s_add_u32 s30, s30, 0x40000
	s_addc_u32 s31, s31, 0
	s_mov_b32 m0, s51
	v_lshl_add_u64 v[224:225], s[30:31], 0, v[134:135]
	ds_read_b128 v[184:187], v151 offset:32768
	ds_read_b128 v[188:191], v151 offset:33792
	ds_read_b128 v[192:195], v151 offset:34816
	ds_read_b128 v[196:199], v151 offset:35840
	ds_read_b128 v[200:203], v151 offset:36864
	ds_read_b128 v[204:207], v151 offset:37888
	ds_read_b128 v[212:215], v151 offset:38912
	ds_read_b128 v[216:219], v151 offset:39936
	global_load_lds_dwordx4 v[224:225], off
	v_lshl_add_u64 v[224:225], s[30:31], 0, v[130:131]
	s_mov_b32 m0, s52
	s_nop 0
	global_load_lds_dwordx4 v[224:225], off
	s_waitcnt vmcnt(8)
	s_waitcnt lgkmcnt(0)
	s_barrier
	s_setprio 1
	s_waitcnt lgkmcnt(0)
	v_mfma_f32_16x16x32_bf16 v[124:127], v[152:155], v[184:187], v[124:127]
	v_mfma_f32_16x16x32_bf16 v[120:123], v[160:163], v[184:187], v[120:123]
	v_mfma_f32_16x16x32_bf16 v[116:119], v[152:155], v[192:195], v[116:119]
	v_mfma_f32_16x16x32_bf16 v[108:111], v[160:163], v[192:195], v[108:111]
	v_mfma_f32_16x16x32_bf16 v[100:103], v[152:155], v[200:203], v[100:103]
	v_mfma_f32_16x16x32_bf16 v[92:95], v[160:163], v[200:203], v[92:95]
	v_mfma_f32_16x16x32_bf16 v[84:87], v[152:155], v[212:215], v[84:87]
	v_mfma_f32_16x16x32_bf16 v[76:79], v[160:163], v[212:215], v[76:79]
	v_mfma_f32_16x16x32_bf16 v[124:127], v[156:159], v[188:191], v[124:127]
	v_mfma_f32_16x16x32_bf16 v[120:123], v[164:167], v[188:191], v[120:123]
	v_mfma_f32_16x16x32_bf16 v[116:119], v[156:159], v[196:199], v[116:119]
	v_mfma_f32_16x16x32_bf16 v[108:111], v[164:167], v[196:199], v[108:111]
	v_mfma_f32_16x16x32_bf16 v[100:103], v[156:159], v[204:207], v[100:103]
	v_mfma_f32_16x16x32_bf16 v[92:95], v[164:167], v[204:207], v[92:95]
	v_mfma_f32_16x16x32_bf16 v[84:87], v[156:159], v[216:219], v[84:87]
	v_mfma_f32_16x16x32_bf16 v[76:79], v[164:167], v[216:219], v[76:79]
	s_setprio 0
	s_setprio 1
	v_mfma_f32_16x16x32_bf16 v[112:115], v[168:171], v[184:187], v[112:115]
	v_mfma_f32_16x16x32_bf16 v[104:107], v[176:179], v[184:187], v[104:107]
	v_mfma_f32_16x16x32_bf16 v[96:99], v[168:171], v[192:195], v[96:99]
	v_mfma_f32_16x16x32_bf16 v[88:91], v[176:179], v[192:195], v[88:91]
	v_mfma_f32_16x16x32_bf16 v[80:83], v[168:171], v[200:203], v[80:83]
	v_mfma_f32_16x16x32_bf16 v[72:75], v[176:179], v[200:203], v[72:75]
	v_mfma_f32_16x16x32_bf16 v[68:71], v[168:171], v[212:215], v[68:71]
	v_mfma_f32_16x16x32_bf16 v[64:67], v[176:179], v[212:215], v[64:67]
	v_mfma_f32_16x16x32_bf16 v[112:115], v[172:175], v[188:191], v[112:115]
	v_mfma_f32_16x16x32_bf16 v[104:107], v[180:183], v[188:191], v[104:107]
	v_mfma_f32_16x16x32_bf16 v[96:99], v[172:175], v[196:199], v[96:99]
	v_mfma_f32_16x16x32_bf16 v[88:91], v[180:183], v[196:199], v[88:91]
	v_mfma_f32_16x16x32_bf16 v[80:83], v[172:175], v[204:207], v[80:83]
	v_mfma_f32_16x16x32_bf16 v[72:75], v[180:183], v[204:207], v[72:75]
	v_mfma_f32_16x16x32_bf16 v[68:71], v[172:175], v[216:219], v[68:71]
	v_mfma_f32_16x16x32_bf16 v[64:67], v[180:183], v[216:219], v[64:67]
	s_setprio 0
	s_barrier
; #define PG8_STAGE(bufoff, gbase, voff) do { _Pragma("unroll") for (int _i = 0; _i < 2; ++_i) \
;         __builtin_amdgcn_global_load_lds((const unsigned*)((const char*)(gbase) + (voff)[_i]), (PG8_LAS unsigned*)(lds + (bufoff) + ldsw + _i * 8192), 16, 0, 0); } while (0)
; #define PG8_LDA(dst, b, h) do { _Pragma("unroll") for (int m = 0; m < 4; ++m) _Pragma("unroll") for (int k = 0; k < 2; ++k) dst[m][k] = *(const PG8_LAS bf16x8*)(lds + PG8_SA(b, h) + aoff + m * 2048 + k * 1024); } while (0)
; #define PG8_MMA(ai, bj, At, Bt) do { __builtin_amdgcn_s_setprio(1); _Pragma("unroll") for (int m = 0; m < 4; ++m) _Pragma("unroll") for (int n = 0; n < 2; ++n) _Pragma("unroll") for (int k = 0; k < 2; ++k) \
;         acc[ai][bj][m][n] = __builtin_amdgcn_mfma_f32_16x16x32_bf16(Bt[n][k], At[m][k], acc[ai][bj][m][n], 0, 0, 0); __builtin_amdgcn_s_setprio(0); } while (0)
; #define PG8_WAIT_V(n) asm volatile("s_waitcnt vmcnt(" #n ")" ::: "memory")
; #define PG8_WAIT_L(n) asm volatile("s_waitcnt lgkmcnt(" #n ")" ::: "memory")
; #define PG8_BAR __builtin_amdgcn_s_barrier()
; #define PG8_SCHED __builtin_amdgcn_sched_barrier(0)
; template <class Epi, class Sched, bool ALIGN_EPI = false, bool SP2 = false, bool AROWS128 = false>
; __device__ __forceinline__ void gemm_phase(PG8_LAS unsigned char* lds, const Gemm g, const Sched& S, const Epi& E) {
;     ...
;         for (int t = 0; t < nt; t += 2) {
;     ...
;             PG8_LDA(At, 1, 1); PG8_STAGE(PG8_SB(1, 0), b3, voffB); PG8_STAGE(PG8_SB(1, 1), b3 + hstep, voffB); PG8_STAGE(PG8_SA(1, 0), a3, voffA);
;             PG8_WAIT_V(8); PG8_WAIT_L(0); PG8_BAR; PG8_MMA(1, 0, At, B0); PG8_MMA(1, 1, At, B1); PG8_BAR; PG8_SCHED;
	s_add_i32 s30, s85, s3
	v_lshl_add_u64 v[144:145], v[144:145], 0, s[6:7]
	s_mov_b32 m0, s30
	ds_read_b128 v[184:187], v151 offset:49152
	ds_read_b128 v[188:191], v151 offset:50176
	ds_read_b128 v[192:195], v151 offset:51200
	ds_read_b128 v[196:199], v151 offset:52224
	ds_read_b128 v[200:203], v151 offset:53248
	ds_read_b128 v[204:207], v151 offset:54272
	ds_read_b128 v[212:215], v151 offset:55296
	ds_read_b128 v[216:219], v151 offset:56320
	global_load_lds_dwordx4 v[144:145], off
	s_add_i32 m0, s30, 0x2000
	s_add_u32 s28, s28, 0x40080
	v_lshl_add_u64 v[144:145], v[208:209], 0, s[6:7]
	s_addc_u32 s29, s29, 0
	s_add_i32 s30, s86, s3
	global_load_lds_dwordx4 v[144:145], off
	v_lshl_add_u64 v[144:145], s[28:29], 0, v[132:133]
	s_mov_b32 m0, s30
	s_nop 0
	global_load_lds_dwordx4 v[144:145], off
	v_lshl_add_u64 v[144:145], s[28:29], 0, v[128:129]
	s_add_i32 m0, s30, 0x2000
	s_nop 0
	global_load_lds_dwordx4 v[144:145], off
	v_lshl_add_u64 v[144:145], v[220:221], 0, s[6:7]
	s_mov_b32 m0, s58
	s_nop 0
	global_load_lds_dwordx4 v[144:145], off
	v_lshl_add_u64 v[144:145], v[222:223], 0, s[6:7]
	s_mov_b32 m0, s59
	s_nop 0
	global_load_lds_dwordx4 v[144:145], off
	s_waitcnt vmcnt(8)
	s_waitcnt lgkmcnt(0)
	s_barrier
	s_setprio 1
	s_waitcnt lgkmcnt(0)
	v_mfma_f32_16x16x32_bf16 v[60:63], v[152:155], v[184:187], v[60:63]
	v_mfma_f32_16x16x32_bf16 v[56:59], v[160:163], v[184:187], v[56:59]
	v_mfma_f32_16x16x32_bf16 v[52:55], v[152:155], v[192:195], v[52:55]
	v_mfma_f32_16x16x32_bf16 v[44:47], v[160:163], v[192:195], v[44:47]
	v_mfma_f32_16x16x32_bf16 v[36:39], v[152:155], v[200:203], v[36:39]
	v_mfma_f32_16x16x32_bf16 v[28:31], v[160:163], v[200:203], v[28:31]
	v_mfma_f32_16x16x32_bf16 v[20:23], v[152:155], v[212:215], v[20:23]
	v_mfma_f32_16x16x32_bf16 v[12:15], v[160:163], v[212:215], v[12:15]
	v_mfma_f32_16x16x32_bf16 v[60:63], v[156:159], v[188:191], v[60:63]
	v_mfma_f32_16x16x32_bf16 v[56:59], v[164:167], v[188:191], v[56:59]
	v_mfma_f32_16x16x32_bf16 v[52:55], v[156:159], v[196:199], v[52:55]
	v_mfma_f32_16x16x32_bf16 v[44:47], v[164:167], v[196:199], v[44:47]
	v_mfma_f32_16x16x32_bf16 v[36:39], v[156:159], v[204:207], v[36:39]
	v_mfma_f32_16x16x32_bf16 v[28:31], v[164:167], v[204:207], v[28:31]
	v_mfma_f32_16x16x32_bf16 v[20:23], v[156:159], v[216:219], v[20:23]
	v_mfma_f32_16x16x32_bf16 v[12:15], v[164:167], v[216:219], v[12:15]
	s_setprio 0
	s_setprio 1
	v_mfma_f32_16x16x32_bf16 v[48:51], v[168:171], v[184:187], v[48:51]
	v_mfma_f32_16x16x32_bf16 v[40:43], v[176:179], v[184:187], v[40:43]
	v_mfma_f32_16x16x32_bf16 v[32:35], v[168:171], v[192:195], v[32:35]
	v_mfma_f32_16x16x32_bf16 v[24:27], v[176:179], v[192:195], v[24:27]
	v_mfma_f32_16x16x32_bf16 v[16:19], v[168:171], v[200:203], v[16:19]
	v_mfma_f32_16x16x32_bf16 v[8:11], v[176:179], v[200:203], v[8:11]
	v_mfma_f32_16x16x32_bf16 v[4:7], v[168:171], v[212:215], v[4:7]
	v_mfma_f32_16x16x32_bf16 v[0:3], v[176:179], v[212:215], v[0:3]
	v_mfma_f32_16x16x32_bf16 v[48:51], v[172:175], v[188:191], v[48:51]
	v_mfma_f32_16x16x32_bf16 v[40:43], v[180:183], v[188:191], v[40:43]
	v_mfma_f32_16x16x32_bf16 v[32:35], v[172:175], v[196:199], v[32:35]
	v_mfma_f32_16x16x32_bf16 v[24:27], v[180:183], v[196:199], v[24:27]
	v_mfma_f32_16x16x32_bf16 v[16:19], v[172:175], v[204:207], v[16:19]
	v_mfma_f32_16x16x32_bf16 v[8:11], v[180:183], v[204:207], v[8:11]
	v_mfma_f32_16x16x32_bf16 v[4:7], v[172:175], v[216:219], v[4:7]
	v_mfma_f32_16x16x32_bf16 v[0:3], v[180:183], v[216:219], v[0:3]
	s_setprio 0
	s_barrier
	s_add_i32 s84, s84, 2
	s_add_u32 s26, s26, 0x100
	s_addc_u32 s27, s27, 0
	s_add_u32 s82, s82, 0x100
	s_addc_u32 s83, s83, 0
	s_cmp_gt_u32 s84, 13
	s_cbranch_scc0 .LBB0_489
	s_and_b64 vcc, exec, s[8:9]
	s_cbranch_vccz .LBB0_492
	s_barrier

; #define PG8_STAGE(bufoff, gbase, voff) do { _Pragma("unroll") for (int _i = 0; _i < 2; ++_i) \
;         __builtin_amdgcn_global_load_lds((const unsigned*)((const char*)(gbase) + (voff)[_i]), (PG8_LAS unsigned*)(lds + (bufoff) + ldsw + _i * 8192), 16, 0, 0); } while (0)
; #define PG8_LDA(dst, b, h) do { _Pragma("unroll") for (int m = 0; m < 4; ++m) _Pragma("unroll") for (int k = 0; k < 2; ++k) dst[m][k] = *(const PG8_LAS bf16x8*)(lds + PG8_SA(b, h) + aoff + m * 2048 + k * 1024); } while (0)
; #define PG8_LDB(dst, b, h) do { _Pragma("unroll") for (int n = 0; n < 2; ++n) _Pragma("unroll") for (int k = 0; k < 2; ++k) dst[n][k] = *(const PG8_LAS bf16x8*)(lds + PG8_SB(b, h) + boff + n * 2048 + k * 1024); } while (0)
; #define PG8_MMA(ai, bj, At, Bt) do { __builtin_amdgcn_s_setprio(1); _Pragma("unroll") for (int m = 0; m < 4; ++m) _Pragma("unroll") for (int n = 0; n < 2; ++n) _Pragma("unroll") for (int k = 0; k < 2; ++k) \
;         acc[ai][bj][m][n] = __builtin_amdgcn_mfma_f32_16x16x32_bf16(Bt[n][k], At[m][k], acc[ai][bj][m][n], 0, 0, 0); __builtin_amdgcn_s_setprio(0); } while (0)
; #define PG8_WAIT_V(n) asm volatile("s_waitcnt vmcnt(" #n ")" ::: "memory")
; #define PG8_WAIT_L(n) asm volatile("s_waitcnt lgkmcnt(" #n ")" ::: "memory")
; #define PG8_BAR __builtin_amdgcn_s_barrier()
; #define PG8_SCHED __builtin_amdgcn_sched_barrier(0)
; template <class Epi, class Sched, bool ALIGN_EPI = false, bool SP2 = false, bool AROWS128 = false>
; __device__ __forceinline__ void gemm_phase(PG8_LAS unsigned char* lds, const Gemm g, const Sched& S, const Epi& E) {
;     ...
;             PG8_LDB(B0, 0, 0); PG8_LDB(B1, 0, 1); PG8_SCHED; PG8_LDA(At, 0, 0); PG8_STAGE(PG8_SA(1, 1), a1 + hstepA, voffA);
;             PG8_WAIT_V(8); PG8_WAIT_L(0); PG8_BAR; PG8_MMA(0, 0, At, B0); PG8_MMA(0, 1, At, B1); PG8_BAR; PG8_SCHED;
;             PG8_LDA(At, 0, 1); PG8_STAGE(PG8_SB(0, 0), b2, voffB); PG8_STAGE(PG8_SB(0, 1), b2 + hstep, voffB); PG8_STAGE(PG8_SA(0, 0), a2, voffA);
.LBB0_626:
	ds_read_b128 v[72:75], v207
	ds_read_b128 v[76:79], v207 offset:1024
	ds_read_b128 v[80:83], v207 offset:2048
	ds_read_b128 v[84:87], v207 offset:3072
	ds_read_b128 v[88:91], v208
	ds_read_b128 v[92:95], v208 offset:1024
	ds_read_b128 v[96:99], v208 offset:2048
	ds_read_b128 v[100:103], v208 offset:3072
	s_add_u32 s20, s18, 0xfffe0080
	s_addc_u32 s21, s19, -1
	s_cmp_eq_u32 s73, 12
	s_cselect_b32 s81, s17, s21
	s_cselect_b32 s80, s33, s20
	s_cselect_b32 s21, s53, s72
	s_cselect_b32 s20, s55, s65
	v_lshl_add_u64 v[220:221], s[18:19], 0, v[168:169]
	s_add_i32 m0, s84, 0xc000
	ds_read_b128 v[176:179], v209
	ds_read_b128 v[180:183], v209 offset:1024
	ds_read_b128 v[184:187], v209 offset:2048
	ds_read_b128 v[188:191], v209 offset:3072
	ds_read_b128 v[192:195], v209 offset:4096
	ds_read_b128 v[196:199], v209 offset:5120
	ds_read_b128 v[212:215], v209 offset:6144
	ds_read_b128 v[216:219], v209 offset:7168
	global_load_lds_dwordx4 v[220:221], off
	v_lshl_add_u64 v[220:221], s[18:19], 0, v[170:171]
	s_add_i32 m0, s84, 0xe000
	s_nop 0
	global_load_lds_dwordx4 v[220:221], off
	s_waitcnt vmcnt(8)
	s_waitcnt lgkmcnt(0)
	s_barrier
	s_setprio 1
	s_waitcnt lgkmcnt(0)
	v_mfma_f32_16x16x32_bf16 v[36:39], v[72:75], v[176:179], v[36:39]
	v_mfma_f32_16x16x32_bf16 v[28:31], v[80:83], v[176:179], v[28:31]
	v_mfma_f32_16x16x32_bf16 v[140:143], v[72:75], v[184:187], v[140:143]
	v_mfma_f32_16x16x32_bf16 v[136:139], v[80:83], v[184:187], v[136:139]
	v_mfma_f32_16x16x32_bf16 v[124:127], v[72:75], v[192:195], v[124:127]
	v_mfma_f32_16x16x32_bf16 v[120:123], v[80:83], v[192:195], v[120:123]
	v_mfma_f32_16x16x32_bf16 v[108:111], v[72:75], v[212:215], v[108:111]
	v_mfma_f32_16x16x32_bf16 v[104:107], v[80:83], v[212:215], v[104:107]
	v_mfma_f32_16x16x32_bf16 v[36:39], v[76:79], v[180:183], v[36:39]
	v_mfma_f32_16x16x32_bf16 v[28:31], v[84:87], v[180:183], v[28:31]
	v_mfma_f32_16x16x32_bf16 v[140:143], v[76:79], v[188:191], v[140:143]
	v_mfma_f32_16x16x32_bf16 v[136:139], v[84:87], v[188:191], v[136:139]
	v_mfma_f32_16x16x32_bf16 v[124:127], v[76:79], v[196:199], v[124:127]
	v_mfma_f32_16x16x32_bf16 v[120:123], v[84:87], v[196:199], v[120:123]
	v_mfma_f32_16x16x32_bf16 v[108:111], v[76:79], v[216:219], v[108:111]
	v_mfma_f32_16x16x32_bf16 v[104:107], v[84:87], v[216:219], v[104:107]
	s_setprio 0
	s_setprio 1
	v_mfma_f32_16x16x32_bf16 v[156:159], v[88:91], v[176:179], v[156:159]
	v_mfma_f32_16x16x32_bf16 v[152:155], v[96:99], v[176:179], v[152:155]
	v_mfma_f32_16x16x32_bf16 v[148:151], v[88:91], v[184:187], v[148:151]
	v_mfma_f32_16x16x32_bf16 v[144:147], v[96:99], v[184:187], v[144:147]
	v_mfma_f32_16x16x32_bf16 v[132:135], v[88:91], v[192:195], v[132:135]
	v_mfma_f32_16x16x32_bf16 v[128:131], v[96:99], v[192:195], v[128:131]
	v_mfma_f32_16x16x32_bf16 v[116:119], v[88:91], v[212:215], v[116:119]
	v_mfma_f32_16x16x32_bf16 v[112:115], v[96:99], v[212:215], v[112:115]
	v_mfma_f32_16x16x32_bf16 v[156:159], v[92:95], v[180:183], v[156:159]
	v_mfma_f32_16x16x32_bf16 v[152:155], v[100:103], v[180:183], v[152:155]
	v_mfma_f32_16x16x32_bf16 v[148:151], v[92:95], v[188:191], v[148:151]
	v_mfma_f32_16x16x32_bf16 v[144:147], v[100:103], v[188:191], v[144:147]
	v_mfma_f32_16x16x32_bf16 v[132:135], v[92:95], v[196:199], v[132:135]
	v_mfma_f32_16x16x32_bf16 v[128:131], v[100:103], v[196:199], v[128:131]
	v_mfma_f32_16x16x32_bf16 v[116:119], v[92:95], v[216:219], v[116:119]
	v_mfma_f32_16x16x32_bf16 v[112:115], v[100:103], v[216:219], v[112:115]
	s_setprio 0
	s_barrier
	s_nop 0
	s_add_i32 s76, s3, s35
	v_lshl_add_u64 v[220:221], s[20:21], 0, v[162:163]
	s_mov_b32 m0, s76
	ds_read_b128 v[176:179], v209 offset:16384
	ds_read_b128 v[180:183], v209 offset:17408
	ds_read_b128 v[184:187], v209 offset:18432
	ds_read_b128 v[188:191], v209 offset:19456
	ds_read_b128 v[192:195], v209 offset:20480
	ds_read_b128 v[196:199], v209 offset:21504
	ds_read_b128 v[212:215], v209 offset:22528
	ds_read_b128 v[216:219], v209 offset:23552
	global_load_lds_dwordx4 v[220:221], off
	s_add_i32 m0, s76, 0x2000
	s_add_u32 s76, s20, 0x40000
	v_lshl_add_u64 v[222:223], s[20:21], 0, v[166:167]
	s_addc_u32 s77, s21, 0
	s_add_i32 s82, s95, s35
	global_load_lds_dwordx4 v[222:223], off
	v_lshl_add_u64 v[224:225], s[76:77], 0, v[162:163]
	s_mov_b32 m0, s82
	v_lshl_add_u64 v[226:227], s[80:81], 0, v[164:165]
	global_load_lds_dwordx4 v[224:225], off
	v_lshl_add_u64 v[224:225], s[76:77], 0, v[166:167]
	s_add_i32 m0, s82, 0x2000
	s_nop 0
	global_load_lds_dwordx4 v[224:225], off
	v_lshl_add_u64 v[224:225], s[80:81], 0, v[160:161]
	s_mov_b32 m0, s84
	s_nop 0
	global_load_lds_dwordx4 v[224:225], off
	s_mov_b32 m0, s85
	s_nop 0
	global_load_lds_dwordx4 v[226:227], off
	s_waitcnt vmcnt(8)
	s_waitcnt lgkmcnt(0)
	s_barrier
; #define PG8_STAGE(bufoff, gbase, voff) do { _Pragma("unroll") for (int _i = 0; _i < 2; ++_i) \
;         __builtin_amdgcn_global_load_lds((const unsigned*)((const char*)(gbase) + (voff)[_i]), (PG8_LAS unsigned*)(lds + (bufoff) + ldsw + _i * 8192), 16, 0, 0); } while (0)
; #define PG8_LDA(dst, b, h) do { _Pragma("unroll") for (int m = 0; m < 4; ++m) _Pragma("unroll") for (int k = 0; k < 2; ++k) dst[m][k] = *(const PG8_LAS bf16x8*)(lds + PG8_SA(b, h) + aoff + m * 2048 + k * 1024); } while (0)
; #define PG8_LDB(dst, b, h) do { _Pragma("unroll") for (int n = 0; n < 2; ++n) _Pragma("unroll") for (int k = 0; k < 2; ++k) dst[n][k] = *(const PG8_LAS bf16x8*)(lds + PG8_SB(b, h) + boff + n * 2048 + k * 1024); } while (0)
; #define PG8_MMA(ai, bj, At, Bt) do { __builtin_amdgcn_s_setprio(1); _Pragma("unroll") for (int m = 0; m < 4; ++m) _Pragma("unroll") for (int n = 0; n < 2; ++n) _Pragma("unroll") for (int k = 0; k < 2; ++k) \
;         acc[ai][bj][m][n] = __builtin_amdgcn_mfma_f32_16x16x32_bf16(Bt[n][k], At[m][k], acc[ai][bj][m][n], 0, 0, 0); __builtin_amdgcn_s_setprio(0); } while (0)
; #define PG8_WAIT_V(n) asm volatile("s_waitcnt vmcnt(" #n ")" ::: "memory")
; #define PG8_WAIT_L(n) asm volatile("s_waitcnt lgkmcnt(" #n ")" ::: "memory")
; #define PG8_BAR __builtin_amdgcn_s_barrier()
; #define PG8_SCHED __builtin_amdgcn_sched_barrier(0)
; template <class Epi, class Sched, bool ALIGN_EPI = false, bool SP2 = false, bool AROWS128 = false>
; __device__ __forceinline__ void gemm_phase(PG8_LAS unsigned char* lds, const Gemm g, const Sched& S, const Epi& E) {
;     ...
;             PG8_WAIT_V(8); PG8_WAIT_L(0); PG8_BAR; PG8_MMA(1, 0, At, B0); PG8_MMA(1, 1, At, B1); PG8_BAR; PG8_SCHED;
;             PG8_LDB(B0, 1, 0); PG8_LDB(B1, 1, 1); PG8_SCHED; PG8_LDA(At, 1, 0); PG8_STAGE(PG8_SA(0, 1), a2 + hstepA, voffA);
;             PG8_WAIT_V(8); PG8_WAIT_L(0); PG8_BAR; PG8_MMA(0, 0, At, B0); PG8_MMA(0, 1, At, B1); PG8_BAR; PG8_SCHED;
	s_setprio 1
	s_waitcnt lgkmcnt(0)
	v_mfma_f32_16x16x32_bf16 v[60:63], v[72:75], v[176:179], v[60:63]
	v_mfma_f32_16x16x32_bf16 v[56:59], v[80:83], v[176:179], v[56:59]
	v_mfma_f32_16x16x32_bf16 v[44:47], v[72:75], v[184:187], v[44:47]
	v_mfma_f32_16x16x32_bf16 v[40:43], v[80:83], v[184:187], v[40:43]
	v_mfma_f32_16x16x32_bf16 v[20:23], v[72:75], v[192:195], v[20:23]
	v_mfma_f32_16x16x32_bf16 v[16:19], v[80:83], v[192:195], v[16:19]
	v_mfma_f32_16x16x32_bf16 v[12:15], v[72:75], v[212:215], v[12:15]
	v_mfma_f32_16x16x32_bf16 v[8:11], v[80:83], v[212:215], v[8:11]
	v_mfma_f32_16x16x32_bf16 v[60:63], v[76:79], v[180:183], v[60:63]
	v_mfma_f32_16x16x32_bf16 v[56:59], v[84:87], v[180:183], v[56:59]
	v_mfma_f32_16x16x32_bf16 v[44:47], v[76:79], v[188:191], v[44:47]
	v_mfma_f32_16x16x32_bf16 v[40:43], v[84:87], v[188:191], v[40:43]
	v_mfma_f32_16x16x32_bf16 v[20:23], v[76:79], v[196:199], v[20:23]
	v_mfma_f32_16x16x32_bf16 v[16:19], v[84:87], v[196:199], v[16:19]
	v_mfma_f32_16x16x32_bf16 v[12:15], v[76:79], v[216:219], v[12:15]
	v_mfma_f32_16x16x32_bf16 v[8:11], v[84:87], v[216:219], v[8:11]
	s_setprio 0
	s_setprio 1
	v_mfma_f32_16x16x32_bf16 v[68:71], v[88:91], v[176:179], v[68:71]
	v_mfma_f32_16x16x32_bf16 v[64:67], v[96:99], v[176:179], v[64:67]
	v_mfma_f32_16x16x32_bf16 v[52:55], v[88:91], v[184:187], v[52:55]
	v_mfma_f32_16x16x32_bf16 v[48:51], v[96:99], v[184:187], v[48:51]
	v_mfma_f32_16x16x32_bf16 v[32:35], v[88:91], v[192:195], v[32:35]
	v_mfma_f32_16x16x32_bf16 v[24:27], v[96:99], v[192:195], v[24:27]
	v_mfma_f32_16x16x32_bf16 v[4:7], v[88:91], v[212:215], v[4:7]
	v_mfma_f32_16x16x32_bf16 v[0:3], v[96:99], v[212:215], v[0:3]
	v_mfma_f32_16x16x32_bf16 v[68:71], v[92:95], v[180:183], v[68:71]
	v_mfma_f32_16x16x32_bf16 v[64:67], v[100:103], v[180:183], v[64:67]
	v_mfma_f32_16x16x32_bf16 v[52:55], v[92:95], v[188:191], v[52:55]
	v_mfma_f32_16x16x32_bf16 v[48:51], v[100:103], v[188:191], v[48:51]
	v_mfma_f32_16x16x32_bf16 v[32:35], v[92:95], v[196:199], v[32:35]
	v_mfma_f32_16x16x32_bf16 v[24:27], v[100:103], v[196:199], v[24:27]
	v_mfma_f32_16x16x32_bf16 v[4:7], v[92:95], v[216:219], v[4:7]
	v_mfma_f32_16x16x32_bf16 v[0:3], v[100:103], v[216:219], v[0:3]
	s_setprio 0
	s_barrier
	s_nop 0
	s_add_i32 s82, 0, 0x18000
	s_add_i32 s83, 0, 0x1c000
	v_add_u32_e32 v84, s82, v200
	v_add_u32_e32 v100, s83, v200
	ds_read_b128 v[72:75], v84
	ds_read_b128 v[76:79], v84 offset:1024
	ds_read_b128 v[80:83], v84 offset:2048
	ds_read_b128 v[84:87], v84 offset:3072
	ds_read_b128 v[88:91], v100
	ds_read_b128 v[92:95], v100 offset:1024
	ds_read_b128 v[96:99], v100 offset:2048
	ds_read_b128 v[100:103], v100 offset:3072
	s_add_u32 s76, s80, 0x20000
	s_addc_u32 s77, s81, 0
	s_mov_b32 m0, s86
	v_lshl_add_u64 v[228:229], s[76:77], 0, v[160:161]
	ds_read_b128 v[176:179], v209 offset:32768
	ds_read_b128 v[180:183], v209 offset:33792
	ds_read_b128 v[184:187], v209 offset:34816
	ds_read_b128 v[188:191], v209 offset:35840
	ds_read_b128 v[192:195], v209 offset:36864
	ds_read_b128 v[196:199], v209 offset:37888
	ds_read_b128 v[212:215], v209 offset:38912
	ds_read_b128 v[216:219], v209 offset:39936
	global_load_lds_dwordx4 v[228:229], off
	v_lshl_add_u64 v[228:229], s[76:77], 0, v[164:165]
	s_mov_b32 m0, s87
	s_nop 0
	global_load_lds_dwordx4 v[228:229], off
	s_waitcnt vmcnt(8)
	s_waitcnt lgkmcnt(0)
	s_barrier
	s_setprio 1
	s_waitcnt lgkmcnt(0)
	v_mfma_f32_16x16x32_bf16 v[36:39], v[72:75], v[176:179], v[36:39]
	v_mfma_f32_16x16x32_bf16 v[28:31], v[80:83], v[176:179], v[28:31]
	v_mfma_f32_16x16x32_bf16 v[140:143], v[72:75], v[184:187], v[140:143]
	v_mfma_f32_16x16x32_bf16 v[136:139], v[80:83], v[184:187], v[136:139]
	v_mfma_f32_16x16x32_bf16 v[124:127], v[72:75], v[192:195], v[124:127]
	v_mfma_f32_16x16x32_bf16 v[120:123], v[80:83], v[192:195], v[120:123]
	v_mfma_f32_16x16x32_bf16 v[108:111], v[72:75], v[212:215], v[108:111]
	v_mfma_f32_16x16x32_bf16 v[104:107], v[80:83], v[212:215], v[104:107]
	v_mfma_f32_16x16x32_bf16 v[36:39], v[76:79], v[180:183], v[36:39]
	v_mfma_f32_16x16x32_bf16 v[28:31], v[84:87], v[180:183], v[28:31]
	v_mfma_f32_16x16x32_bf16 v[140:143], v[76:79], v[188:191], v[140:143]
	v_mfma_f32_16x16x32_bf16 v[136:139], v[84:87], v[188:191], v[136:139]
	v_mfma_f32_16x16x32_bf16 v[124:127], v[76:79], v[196:199], v[124:127]
	v_mfma_f32_16x16x32_bf16 v[120:123], v[84:87], v[196:199], v[120:123]
	v_mfma_f32_16x16x32_bf16 v[108:111], v[76:79], v[216:219], v[108:111]
	v_mfma_f32_16x16x32_bf16 v[104:107], v[84:87], v[216:219], v[104:107]
	s_setprio 0
	s_setprio 1
	v_mfma_f32_16x16x32_bf16 v[156:159], v[88:91], v[176:179], v[156:159]
	v_mfma_f32_16x16x32_bf16 v[152:155], v[96:99], v[176:179], v[152:155]
	v_mfma_f32_16x16x32_bf16 v[148:151], v[88:91], v[184:187], v[148:151]
	v_mfma_f32_16x16x32_bf16 v[144:147], v[96:99], v[184:187], v[144:147]
	v_mfma_f32_16x16x32_bf16 v[132:135], v[88:91], v[192:195], v[132:135]
	v_mfma_f32_16x16x32_bf16 v[128:131], v[96:99], v[192:195], v[128:131]
	v_mfma_f32_16x16x32_bf16 v[116:119], v[88:91], v[212:215], v[116:119]
	v_mfma_f32_16x16x32_bf16 v[112:115], v[96:99], v[212:215], v[112:115]
	v_mfma_f32_16x16x32_bf16 v[156:159], v[92:95], v[180:183], v[156:159]
	v_mfma_f32_16x16x32_bf16 v[152:155], v[100:103], v[180:183], v[152:155]
	v_mfma_f32_16x16x32_bf16 v[148:151], v[92:95], v[188:191], v[148:151]
	v_mfma_f32_16x16x32_bf16 v[144:147], v[100:103], v[188:191], v[144:147]
	v_mfma_f32_16x16x32_bf16 v[132:135], v[92:95], v[196:199], v[132:135]
	v_mfma_f32_16x16x32_bf16 v[128:131], v[100:103], v[196:199], v[128:131]
	v_mfma_f32_16x16x32_bf16 v[116:119], v[92:95], v[216:219], v[116:119]
	v_mfma_f32_16x16x32_bf16 v[112:115], v[100:103], v[216:219], v[112:115]
	s_setprio 0
	s_barrier
; #define PG8_STAGE(bufoff, gbase, voff) do { _Pragma("unroll") for (int _i = 0; _i < 2; ++_i) \
;         __builtin_amdgcn_global_load_lds((const unsigned*)((const char*)(gbase) + (voff)[_i]), (PG8_LAS unsigned*)(lds + (bufoff) + ldsw + _i * 8192), 16, 0, 0); } while (0)
; #define PG8_LDA(dst, b, h) do { _Pragma("unroll") for (int m = 0; m < 4; ++m) _Pragma("unroll") for (int k = 0; k < 2; ++k) dst[m][k] = *(const PG8_LAS bf16x8*)(lds + PG8_SA(b, h) + aoff + m * 2048 + k * 1024); } while (0)
; #define PG8_MMA(ai, bj, At, Bt) do { __builtin_amdgcn_s_setprio(1); _Pragma("unroll") for (int m = 0; m < 4; ++m) _Pragma("unroll") for (int n = 0; n < 2; ++n) _Pragma("unroll") for (int k = 0; k < 2; ++k) \
;         acc[ai][bj][m][n] = __builtin_amdgcn_mfma_f32_16x16x32_bf16(Bt[n][k], At[m][k], acc[ai][bj][m][n], 0, 0, 0); __builtin_amdgcn_s_setprio(0); } while (0)
; #define PG8_WAIT_V(n) asm volatile("s_waitcnt vmcnt(" #n ")" ::: "memory")
; #define PG8_WAIT_L(n) asm volatile("s_waitcnt lgkmcnt(" #n ")" ::: "memory")
; #define PG8_BAR __builtin_amdgcn_s_barrier()
; #define PG8_SCHED __builtin_amdgcn_sched_barrier(0)
; template <class Epi, class Sched, bool ALIGN_EPI = false, bool SP2 = false, bool AROWS128 = false>
; __device__ __forceinline__ void gemm_phase(PG8_LAS unsigned char* lds, const Gemm g, const Sched& S, const Epi& E) {
;     ...
;         for (int t = 0; t < nt; t += 2) {
;     ...
;             PG8_LDA(At, 1, 1); PG8_STAGE(PG8_SB(1, 0), b3, voffB); PG8_STAGE(PG8_SB(1, 1), b3 + hstep, voffB); PG8_STAGE(PG8_SA(1, 0), a3, voffA);
;             PG8_WAIT_V(8); PG8_WAIT_L(0); PG8_BAR; PG8_MMA(1, 0, At, B0); PG8_MMA(1, 1, At, B1); PG8_BAR; PG8_SCHED;
	s_add_i32 s76, s82, s35
	v_lshl_add_u64 v[220:221], v[220:221], 0, s[26:27]
	s_mov_b32 m0, s76
	ds_read_b128 v[176:179], v209 offset:49152
	ds_read_b128 v[180:183], v209 offset:50176
	ds_read_b128 v[184:187], v209 offset:51200
	ds_read_b128 v[188:191], v209 offset:52224
	ds_read_b128 v[192:195], v209 offset:53248
	ds_read_b128 v[196:199], v209 offset:54272
	ds_read_b128 v[212:215], v209 offset:55296
	ds_read_b128 v[216:219], v209 offset:56320
	global_load_lds_dwordx4 v[220:221], off
	s_add_i32 m0, s76, 0x2000
	s_add_u32 s20, s20, 0x40080
	v_lshl_add_u64 v[220:221], v[222:223], 0, s[26:27]
	s_addc_u32 s21, s21, 0
	s_add_i32 s76, s83, s35
	global_load_lds_dwordx4 v[220:221], off
	v_lshl_add_u64 v[220:221], s[20:21], 0, v[162:163]
	s_mov_b32 m0, s76
	s_nop 0
	global_load_lds_dwordx4 v[220:221], off
	v_lshl_add_u64 v[220:221], s[20:21], 0, v[166:167]
	s_add_i32 m0, s76, 0x2000
	s_nop 0
	global_load_lds_dwordx4 v[220:221], off
	v_lshl_add_u64 v[220:221], v[224:225], 0, s[26:27]
	s_mov_b32 m0, s89
	s_nop 0
	global_load_lds_dwordx4 v[220:221], off
	v_lshl_add_u64 v[220:221], v[226:227], 0, s[26:27]
	s_mov_b32 m0, s90
	s_nop 0
	global_load_lds_dwordx4 v[220:221], off
	s_waitcnt vmcnt(8)
	s_waitcnt lgkmcnt(0)
	s_barrier
	s_setprio 1
	s_waitcnt lgkmcnt(0)
	v_mfma_f32_16x16x32_bf16 v[60:63], v[72:75], v[176:179], v[60:63]
	v_mfma_f32_16x16x32_bf16 v[56:59], v[80:83], v[176:179], v[56:59]
	v_mfma_f32_16x16x32_bf16 v[44:47], v[72:75], v[184:187], v[44:47]
	v_mfma_f32_16x16x32_bf16 v[40:43], v[80:83], v[184:187], v[40:43]
	v_mfma_f32_16x16x32_bf16 v[20:23], v[72:75], v[192:195], v[20:23]
	v_mfma_f32_16x16x32_bf16 v[16:19], v[80:83], v[192:195], v[16:19]
	v_mfma_f32_16x16x32_bf16 v[12:15], v[72:75], v[212:215], v[12:15]
	v_mfma_f32_16x16x32_bf16 v[8:11], v[80:83], v[212:215], v[8:11]
	v_mfma_f32_16x16x32_bf16 v[60:63], v[76:79], v[180:183], v[60:63]
	v_mfma_f32_16x16x32_bf16 v[56:59], v[84:87], v[180:183], v[56:59]
	v_mfma_f32_16x16x32_bf16 v[44:47], v[76:79], v[188:191], v[44:47]
	v_mfma_f32_16x16x32_bf16 v[40:43], v[84:87], v[188:191], v[40:43]
	v_mfma_f32_16x16x32_bf16 v[20:23], v[76:79], v[196:199], v[20:23]
	v_mfma_f32_16x16x32_bf16 v[16:19], v[84:87], v[196:199], v[16:19]
	v_mfma_f32_16x16x32_bf16 v[12:15], v[76:79], v[216:219], v[12:15]
	v_mfma_f32_16x16x32_bf16 v[8:11], v[84:87], v[216:219], v[8:11]
	s_setprio 0
	s_setprio 1
	v_mfma_f32_16x16x32_bf16 v[68:71], v[88:91], v[176:179], v[68:71]
	v_mfma_f32_16x16x32_bf16 v[64:67], v[96:99], v[176:179], v[64:67]
	v_mfma_f32_16x16x32_bf16 v[52:55], v[88:91], v[184:187], v[52:55]
	v_mfma_f32_16x16x32_bf16 v[48:51], v[96:99], v[184:187], v[48:51]
	v_mfma_f32_16x16x32_bf16 v[32:35], v[88:91], v[192:195], v[32:35]
	v_mfma_f32_16x16x32_bf16 v[24:27], v[96:99], v[192:195], v[24:27]
	v_mfma_f32_16x16x32_bf16 v[4:7], v[88:91], v[212:215], v[4:7]
	v_mfma_f32_16x16x32_bf16 v[0:3], v[96:99], v[212:215], v[0:3]
	v_mfma_f32_16x16x32_bf16 v[68:71], v[92:95], v[180:183], v[68:71]
	v_mfma_f32_16x16x32_bf16 v[64:67], v[100:103], v[180:183], v[64:67]
	v_mfma_f32_16x16x32_bf16 v[52:55], v[92:95], v[188:191], v[52:55]
	v_mfma_f32_16x16x32_bf16 v[48:51], v[100:103], v[188:191], v[48:51]
	v_mfma_f32_16x16x32_bf16 v[32:35], v[92:95], v[196:199], v[32:35]
	v_mfma_f32_16x16x32_bf16 v[24:27], v[100:103], v[196:199], v[24:27]
	v_mfma_f32_16x16x32_bf16 v[4:7], v[92:95], v[216:219], v[4:7]
	v_mfma_f32_16x16x32_bf16 v[0:3], v[100:103], v[216:219], v[0:3]
	s_setprio 0
	s_barrier
	s_add_i32 s73, s73, 2
	s_add_u32 s18, s18, 0x100
	s_addc_u32 s19, s19, 0
	s_add_u32 s65, s65, 0x100
	s_addc_u32 s72, s72, 0
	s_cmp_gt_u32 s73, 13
	s_cbranch_scc0 .LBB0_626
	s_and_b64 vcc, exec, s[28:29]
	s_cbranch_vccz .LBB0_629
	s_barrier

; #define PG8_STAGE(bufoff, gbase, voff) do { _Pragma("unroll") for (int _i = 0; _i < 2; ++_i) \
;         __builtin_amdgcn_global_load_lds((const unsigned*)((const char*)(gbase) + (voff)[_i]), (PG8_LAS unsigned*)(lds + (bufoff) + ldsw + _i * 8192), 16, 0, 0); } while (0)
; #define PG8_LDA(dst, b, h) do { _Pragma("unroll") for (int m = 0; m < 4; ++m) _Pragma("unroll") for (int k = 0; k < 2; ++k) dst[m][k] = *(const PG8_LAS bf16x8*)(lds + PG8_SA(b, h) + aoff + m * 2048 + k * 1024); } while (0)
; #define PG8_LDB(dst, b, h) do { _Pragma("unroll") for (int n = 0; n < 2; ++n) _Pragma("unroll") for (int k = 0; k < 2; ++k) dst[n][k] = *(const PG8_LAS bf16x8*)(lds + PG8_SB(b, h) + boff + n * 2048 + k * 1024); } while (0)
; #define PG8_MMA(ai, bj, At, Bt) do { __builtin_amdgcn_s_setprio(1); _Pragma("unroll") for (int m = 0; m < 4; ++m) _Pragma("unroll") for (int n = 0; n < 2; ++n) _Pragma("unroll") for (int k = 0; k < 2; ++k) \
;         acc[ai][bj][m][n] = __builtin_amdgcn_mfma_f32_16x16x32_bf16(Bt[n][k], At[m][k], acc[ai][bj][m][n], 0, 0, 0); __builtin_amdgcn_s_setprio(0); } while (0)
; #define PG8_WAIT_V(n) asm volatile("s_waitcnt vmcnt(" #n ")" ::: "memory")
; #define PG8_WAIT_L(n) asm volatile("s_waitcnt lgkmcnt(" #n ")" ::: "memory")
; #define PG8_BAR __builtin_amdgcn_s_barrier()
; #define PG8_SCHED __builtin_amdgcn_sched_barrier(0)
; template <class Epi, class Sched, bool ALIGN_EPI = false, bool SP2 = false, bool AROWS128 = false>
; __device__ __forceinline__ void gemm_phase(PG8_LAS unsigned char* lds, const Gemm g, const Sched& S, const Epi& E) {
;     ...
;             PG8_LDB(B0, 0, 0); PG8_LDB(B1, 0, 1); PG8_SCHED; PG8_LDA(At, 0, 0); PG8_STAGE(PG8_SA(1, 1), a1 + hstepA, voffA);
;             PG8_WAIT_V(8); PG8_WAIT_L(0); PG8_BAR; PG8_MMA(0, 0, At, B0); PG8_MMA(0, 1, At, B1); PG8_BAR; PG8_SCHED;
;             PG8_LDA(At, 0, 1); PG8_STAGE(PG8_SB(0, 0), b2, voffB); PG8_STAGE(PG8_SB(0, 1), b2 + hstep, voffB); PG8_STAGE(PG8_SA(0, 0), a2, voffA);
.LBB0_752:
	ds_read_b128 v[152:155], v149
	ds_read_b128 v[156:159], v149 offset:1024
	ds_read_b128 v[160:163], v149 offset:2048
	ds_read_b128 v[164:167], v149 offset:3072
	ds_read_b128 v[168:171], v150
	ds_read_b128 v[172:175], v150 offset:1024
	ds_read_b128 v[176:179], v150 offset:2048
	ds_read_b128 v[180:183], v150 offset:3072
	s_add_u32 s38, s36, 0xfff00080
	s_addc_u32 s39, s37, -1
	s_cmp_eq_u32 s77, 60
	s_cselect_b32 s49, s25, s39
	s_cselect_b32 s48, s65, s38
	s_cselect_b32 s39, s21, s76
	s_cselect_b32 s38, s72, s73
	v_lshl_add_u64 v[144:145], s[36:37], 0, v[136:137]
	s_add_i32 m0, s31, 0xc000
	ds_read_b128 v[184:187], v151
	ds_read_b128 v[188:191], v151 offset:1024
	ds_read_b128 v[192:195], v151 offset:2048
	ds_read_b128 v[196:199], v151 offset:3072
	ds_read_b128 v[200:203], v151 offset:4096
	ds_read_b128 v[204:207], v151 offset:5120
	ds_read_b128 v[212:215], v151 offset:6144
	ds_read_b128 v[216:219], v151 offset:7168
	global_load_lds_dwordx4 v[144:145], off
	v_lshl_add_u64 v[144:145], s[36:37], 0, v[138:139]
	s_add_i32 m0, s31, 0xe000
	s_nop 0
	global_load_lds_dwordx4 v[144:145], off
	s_waitcnt vmcnt(8)
	s_waitcnt lgkmcnt(0)
	s_barrier
	s_setprio 1
	s_waitcnt lgkmcnt(0)
	v_mfma_f32_16x16x32_bf16 v[124:127], v[152:155], v[184:187], v[124:127]
	v_mfma_f32_16x16x32_bf16 v[120:123], v[160:163], v[184:187], v[120:123]
	v_mfma_f32_16x16x32_bf16 v[116:119], v[152:155], v[192:195], v[116:119]
	v_mfma_f32_16x16x32_bf16 v[108:111], v[160:163], v[192:195], v[108:111]
	v_mfma_f32_16x16x32_bf16 v[100:103], v[152:155], v[200:203], v[100:103]
	v_mfma_f32_16x16x32_bf16 v[92:95], v[160:163], v[200:203], v[92:95]
	v_mfma_f32_16x16x32_bf16 v[84:87], v[152:155], v[212:215], v[84:87]
	v_mfma_f32_16x16x32_bf16 v[76:79], v[160:163], v[212:215], v[76:79]
	v_mfma_f32_16x16x32_bf16 v[124:127], v[156:159], v[188:191], v[124:127]
	v_mfma_f32_16x16x32_bf16 v[120:123], v[164:167], v[188:191], v[120:123]
	v_mfma_f32_16x16x32_bf16 v[116:119], v[156:159], v[196:199], v[116:119]
	v_mfma_f32_16x16x32_bf16 v[108:111], v[164:167], v[196:199], v[108:111]
	v_mfma_f32_16x16x32_bf16 v[100:103], v[156:159], v[204:207], v[100:103]
	v_mfma_f32_16x16x32_bf16 v[92:95], v[164:167], v[204:207], v[92:95]
	v_mfma_f32_16x16x32_bf16 v[84:87], v[156:159], v[216:219], v[84:87]
	v_mfma_f32_16x16x32_bf16 v[76:79], v[164:167], v[216:219], v[76:79]
	s_setprio 0
	s_setprio 1
	v_mfma_f32_16x16x32_bf16 v[112:115], v[168:171], v[184:187], v[112:115]
	v_mfma_f32_16x16x32_bf16 v[104:107], v[176:179], v[184:187], v[104:107]
	v_mfma_f32_16x16x32_bf16 v[96:99], v[168:171], v[192:195], v[96:99]
	v_mfma_f32_16x16x32_bf16 v[88:91], v[176:179], v[192:195], v[88:91]
	v_mfma_f32_16x16x32_bf16 v[80:83], v[168:171], v[200:203], v[80:83]
	v_mfma_f32_16x16x32_bf16 v[72:75], v[176:179], v[200:203], v[72:75]
	v_mfma_f32_16x16x32_bf16 v[68:71], v[168:171], v[212:215], v[68:71]
	v_mfma_f32_16x16x32_bf16 v[64:67], v[176:179], v[212:215], v[64:67]
	v_mfma_f32_16x16x32_bf16 v[112:115], v[172:175], v[188:191], v[112:115]
	v_mfma_f32_16x16x32_bf16 v[104:107], v[180:183], v[188:191], v[104:107]
	v_mfma_f32_16x16x32_bf16 v[96:99], v[172:175], v[196:199], v[96:99]
	v_mfma_f32_16x16x32_bf16 v[88:91], v[180:183], v[196:199], v[88:91]
	v_mfma_f32_16x16x32_bf16 v[80:83], v[172:175], v[204:207], v[80:83]
	v_mfma_f32_16x16x32_bf16 v[72:75], v[180:183], v[204:207], v[72:75]
	v_mfma_f32_16x16x32_bf16 v[68:71], v[172:175], v[216:219], v[68:71]
	v_mfma_f32_16x16x32_bf16 v[64:67], v[180:183], v[216:219], v[64:67]
	s_setprio 0
	s_barrier
	s_nop 0
	s_add_i32 s78, s58, s3
	v_lshl_add_u64 v[144:145], s[38:39], 0, v[132:133]
	s_mov_b32 m0, s78
	ds_read_b128 v[184:187], v151 offset:16384
	ds_read_b128 v[188:191], v151 offset:17408
	ds_read_b128 v[192:195], v151 offset:18432
	ds_read_b128 v[196:199], v151 offset:19456
	ds_read_b128 v[200:203], v151 offset:20480
	ds_read_b128 v[204:207], v151 offset:21504
	ds_read_b128 v[212:215], v151 offset:22528
	ds_read_b128 v[216:219], v151 offset:23552
	global_load_lds_dwordx4 v[144:145], off
	s_add_i32 m0, s78, 0x2000
	s_add_u32 s78, s38, 0x100000
	v_lshl_add_u64 v[208:209], s[38:39], 0, v[128:129]
	s_addc_u32 s79, s39, 0
	s_add_i32 s80, s59, s3
	global_load_lds_dwordx4 v[208:209], off
	v_lshl_add_u64 v[220:221], s[78:79], 0, v[132:133]
	s_mov_b32 m0, s80
	v_lshl_add_u64 v[222:223], s[48:49], 0, v[130:131]
	global_load_lds_dwordx4 v[220:221], off
	v_lshl_add_u64 v[220:221], s[78:79], 0, v[128:129]
	s_add_i32 m0, s80, 0x2000
	s_nop 0
	global_load_lds_dwordx4 v[220:221], off
	v_lshl_add_u64 v[220:221], s[48:49], 0, v[134:135]
	s_mov_b32 m0, s31
	s_nop 0
	global_load_lds_dwordx4 v[220:221], off
	s_mov_b32 m0, s50
	s_nop 0
	global_load_lds_dwordx4 v[222:223], off
	s_waitcnt vmcnt(8)
	s_waitcnt lgkmcnt(0)
	s_barrier
; #define PG8_STAGE(bufoff, gbase, voff) do { _Pragma("unroll") for (int _i = 0; _i < 2; ++_i) \
;         __builtin_amdgcn_global_load_lds((const unsigned*)((const char*)(gbase) + (voff)[_i]), (PG8_LAS unsigned*)(lds + (bufoff) + ldsw + _i * 8192), 16, 0, 0); } while (0)
; #define PG8_LDA(dst, b, h) do { _Pragma("unroll") for (int m = 0; m < 4; ++m) _Pragma("unroll") for (int k = 0; k < 2; ++k) dst[m][k] = *(const PG8_LAS bf16x8*)(lds + PG8_SA(b, h) + aoff + m * 2048 + k * 1024); } while (0)
; #define PG8_LDB(dst, b, h) do { _Pragma("unroll") for (int n = 0; n < 2; ++n) _Pragma("unroll") for (int k = 0; k < 2; ++k) dst[n][k] = *(const PG8_LAS bf16x8*)(lds + PG8_SB(b, h) + boff + n * 2048 + k * 1024); } while (0)
; #define PG8_MMA(ai, bj, At, Bt) do { __builtin_amdgcn_s_setprio(1); _Pragma("unroll") for (int m = 0; m < 4; ++m) _Pragma("unroll") for (int n = 0; n < 2; ++n) _Pragma("unroll") for (int k = 0; k < 2; ++k) \
;         acc[ai][bj][m][n] = __builtin_amdgcn_mfma_f32_16x16x32_bf16(Bt[n][k], At[m][k], acc[ai][bj][m][n], 0, 0, 0); __builtin_amdgcn_s_setprio(0); } while (0)
; #define PG8_WAIT_V(n) asm volatile("s_waitcnt vmcnt(" #n ")" ::: "memory")
; #define PG8_WAIT_L(n) asm volatile("s_waitcnt lgkmcnt(" #n ")" ::: "memory")
; #define PG8_BAR __builtin_amdgcn_s_barrier()
; #define PG8_SCHED __builtin_amdgcn_sched_barrier(0)
; template <class Epi, class Sched, bool ALIGN_EPI = false, bool SP2 = false, bool AROWS128 = false>
; __device__ __forceinline__ void gemm_phase(PG8_LAS unsigned char* lds, const Gemm g, const Sched& S, const Epi& E) {
;     ...
;             PG8_WAIT_V(8); PG8_WAIT_L(0); PG8_BAR; PG8_MMA(1, 0, At, B0); PG8_MMA(1, 1, At, B1); PG8_BAR; PG8_SCHED;
;             PG8_LDB(B0, 1, 0); PG8_LDB(B1, 1, 1); PG8_SCHED; PG8_LDA(At, 1, 0); PG8_STAGE(PG8_SA(0, 1), a2 + hstepA, voffA);
;             PG8_WAIT_V(8); PG8_WAIT_L(0); PG8_BAR; PG8_MMA(0, 0, At, B0); PG8_MMA(0, 1, At, B1); PG8_BAR; PG8_SCHED;
	s_setprio 1
	s_waitcnt lgkmcnt(0)
	v_mfma_f32_16x16x32_bf16 v[60:63], v[152:155], v[184:187], v[60:63]
	v_mfma_f32_16x16x32_bf16 v[56:59], v[160:163], v[184:187], v[56:59]
	v_mfma_f32_16x16x32_bf16 v[52:55], v[152:155], v[192:195], v[52:55]
	v_mfma_f32_16x16x32_bf16 v[44:47], v[160:163], v[192:195], v[44:47]
	v_mfma_f32_16x16x32_bf16 v[36:39], v[152:155], v[200:203], v[36:39]
	v_mfma_f32_16x16x32_bf16 v[28:31], v[160:163], v[200:203], v[28:31]
	v_mfma_f32_16x16x32_bf16 v[20:23], v[152:155], v[212:215], v[20:23]
	v_mfma_f32_16x16x32_bf16 v[12:15], v[160:163], v[212:215], v[12:15]
	v_mfma_f32_16x16x32_bf16 v[60:63], v[156:159], v[188:191], v[60:63]
	v_mfma_f32_16x16x32_bf16 v[56:59], v[164:167], v[188:191], v[56:59]
	v_mfma_f32_16x16x32_bf16 v[52:55], v[156:159], v[196:199], v[52:55]
	v_mfma_f32_16x16x32_bf16 v[44:47], v[164:167], v[196:199], v[44:47]
	v_mfma_f32_16x16x32_bf16 v[36:39], v[156:159], v[204:207], v[36:39]
	v_mfma_f32_16x16x32_bf16 v[28:31], v[164:167], v[204:207], v[28:31]
	v_mfma_f32_16x16x32_bf16 v[20:23], v[156:159], v[216:219], v[20:23]
	v_mfma_f32_16x16x32_bf16 v[12:15], v[164:167], v[216:219], v[12:15]
	s_setprio 0
	s_setprio 1
	v_mfma_f32_16x16x32_bf16 v[48:51], v[168:171], v[184:187], v[48:51]
	v_mfma_f32_16x16x32_bf16 v[40:43], v[176:179], v[184:187], v[40:43]
	v_mfma_f32_16x16x32_bf16 v[32:35], v[168:171], v[192:195], v[32:35]
	v_mfma_f32_16x16x32_bf16 v[24:27], v[176:179], v[192:195], v[24:27]
	v_mfma_f32_16x16x32_bf16 v[16:19], v[168:171], v[200:203], v[16:19]
	v_mfma_f32_16x16x32_bf16 v[8:11], v[176:179], v[200:203], v[8:11]
	v_mfma_f32_16x16x32_bf16 v[4:7], v[168:171], v[212:215], v[4:7]
	v_mfma_f32_16x16x32_bf16 v[0:3], v[176:179], v[212:215], v[0:3]
	v_mfma_f32_16x16x32_bf16 v[48:51], v[172:175], v[188:191], v[48:51]
	v_mfma_f32_16x16x32_bf16 v[40:43], v[180:183], v[188:191], v[40:43]
	v_mfma_f32_16x16x32_bf16 v[32:35], v[172:175], v[196:199], v[32:35]
	v_mfma_f32_16x16x32_bf16 v[24:27], v[180:183], v[196:199], v[24:27]
	v_mfma_f32_16x16x32_bf16 v[16:19], v[172:175], v[204:207], v[16:19]
	v_mfma_f32_16x16x32_bf16 v[8:11], v[180:183], v[204:207], v[8:11]
	v_mfma_f32_16x16x32_bf16 v[4:7], v[172:175], v[216:219], v[4:7]
	v_mfma_f32_16x16x32_bf16 v[0:3], v[180:183], v[216:219], v[0:3]
	s_setprio 0
	s_barrier
	s_nop 0
	s_add_i32 s78, 0, 0x18000
	s_add_i32 s79, 0, 0x1c000
	v_add_u32_e32 v164, s78, v147
	v_add_u32_e32 v180, s79, v147
	ds_read_b128 v[152:155], v164
	ds_read_b128 v[156:159], v164 offset:1024
	ds_read_b128 v[160:163], v164 offset:2048
	ds_read_b128 v[164:167], v164 offset:3072
	ds_read_b128 v[168:171], v180
	ds_read_b128 v[172:175], v180 offset:1024
	ds_read_b128 v[176:179], v180 offset:2048
	ds_read_b128 v[180:183], v180 offset:3072
	s_add_u32 s48, s48, 0x100000
	s_addc_u32 s49, s49, 0
	s_mov_b32 m0, s51
	v_lshl_add_u64 v[224:225], s[48:49], 0, v[134:135]
	ds_read_b128 v[184:187], v151 offset:32768
	ds_read_b128 v[188:191], v151 offset:33792
	ds_read_b128 v[192:195], v151 offset:34816
	ds_read_b128 v[196:199], v151 offset:35840
	ds_read_b128 v[200:203], v151 offset:36864
	ds_read_b128 v[204:207], v151 offset:37888
	ds_read_b128 v[212:215], v151 offset:38912
	ds_read_b128 v[216:219], v151 offset:39936
	global_load_lds_dwordx4 v[224:225], off
	v_lshl_add_u64 v[224:225], s[48:49], 0, v[130:131]
	s_mov_b32 m0, s52
	s_nop 0
	global_load_lds_dwordx4 v[224:225], off
	s_waitcnt vmcnt(8)
	s_waitcnt lgkmcnt(0)
	s_barrier
	s_setprio 1
	s_waitcnt lgkmcnt(0)
	v_mfma_f32_16x16x32_bf16 v[124:127], v[152:155], v[184:187], v[124:127]
	v_mfma_f32_16x16x32_bf16 v[120:123], v[160:163], v[184:187], v[120:123]
	v_mfma_f32_16x16x32_bf16 v[116:119], v[152:155], v[192:195], v[116:119]
	v_mfma_f32_16x16x32_bf16 v[108:111], v[160:163], v[192:195], v[108:111]
	v_mfma_f32_16x16x32_bf16 v[100:103], v[152:155], v[200:203], v[100:103]
	v_mfma_f32_16x16x32_bf16 v[92:95], v[160:163], v[200:203], v[92:95]
	v_mfma_f32_16x16x32_bf16 v[84:87], v[152:155], v[212:215], v[84:87]
	v_mfma_f32_16x16x32_bf16 v[76:79], v[160:163], v[212:215], v[76:79]
	v_mfma_f32_16x16x32_bf16 v[124:127], v[156:159], v[188:191], v[124:127]
	v_mfma_f32_16x16x32_bf16 v[120:123], v[164:167], v[188:191], v[120:123]
	v_mfma_f32_16x16x32_bf16 v[116:119], v[156:159], v[196:199], v[116:119]
	v_mfma_f32_16x16x32_bf16 v[108:111], v[164:167], v[196:199], v[108:111]
	v_mfma_f32_16x16x32_bf16 v[100:103], v[156:159], v[204:207], v[100:103]
	v_mfma_f32_16x16x32_bf16 v[92:95], v[164:167], v[204:207], v[92:95]
	v_mfma_f32_16x16x32_bf16 v[84:87], v[156:159], v[216:219], v[84:87]
	v_mfma_f32_16x16x32_bf16 v[76:79], v[164:167], v[216:219], v[76:79]
	s_setprio 0
	s_setprio 1
	v_mfma_f32_16x16x32_bf16 v[112:115], v[168:171], v[184:187], v[112:115]
	v_mfma_f32_16x16x32_bf16 v[104:107], v[176:179], v[184:187], v[104:107]
	v_mfma_f32_16x16x32_bf16 v[96:99], v[168:171], v[192:195], v[96:99]
	v_mfma_f32_16x16x32_bf16 v[88:91], v[176:179], v[192:195], v[88:91]
	v_mfma_f32_16x16x32_bf16 v[80:83], v[168:171], v[200:203], v[80:83]
	v_mfma_f32_16x16x32_bf16 v[72:75], v[176:179], v[200:203], v[72:75]
	v_mfma_f32_16x16x32_bf16 v[68:71], v[168:171], v[212:215], v[68:71]
	v_mfma_f32_16x16x32_bf16 v[64:67], v[176:179], v[212:215], v[64:67]
	v_mfma_f32_16x16x32_bf16 v[112:115], v[172:175], v[188:191], v[112:115]
	v_mfma_f32_16x16x32_bf16 v[104:107], v[180:183], v[188:191], v[104:107]
	v_mfma_f32_16x16x32_bf16 v[96:99], v[172:175], v[196:199], v[96:99]
	v_mfma_f32_16x16x32_bf16 v[88:91], v[180:183], v[196:199], v[88:91]
	v_mfma_f32_16x16x32_bf16 v[80:83], v[172:175], v[204:207], v[80:83]
	v_mfma_f32_16x16x32_bf16 v[72:75], v[180:183], v[204:207], v[72:75]
	v_mfma_f32_16x16x32_bf16 v[68:71], v[172:175], v[216:219], v[68:71]
	v_mfma_f32_16x16x32_bf16 v[64:67], v[180:183], v[216:219], v[64:67]
	s_setprio 0
	s_barrier
; #define PG8_STAGE(bufoff, gbase, voff) do { _Pragma("unroll") for (int _i = 0; _i < 2; ++_i) \
;         __builtin_amdgcn_global_load_lds((const unsigned*)((const char*)(gbase) + (voff)[_i]), (PG8_LAS unsigned*)(lds + (bufoff) + ldsw + _i * 8192), 16, 0, 0); } while (0)
; #define PG8_LDA(dst, b, h) do { _Pragma("unroll") for (int m = 0; m < 4; ++m) _Pragma("unroll") for (int k = 0; k < 2; ++k) dst[m][k] = *(const PG8_LAS bf16x8*)(lds + PG8_SA(b, h) + aoff + m * 2048 + k * 1024); } while (0)
; #define PG8_MMA(ai, bj, At, Bt) do { __builtin_amdgcn_s_setprio(1); _Pragma("unroll") for (int m = 0; m < 4; ++m) _Pragma("unroll") for (int n = 0; n < 2; ++n) _Pragma("unroll") for (int k = 0; k < 2; ++k) \
;         acc[ai][bj][m][n] = __builtin_amdgcn_mfma_f32_16x16x32_bf16(Bt[n][k], At[m][k], acc[ai][bj][m][n], 0, 0, 0); __builtin_amdgcn_s_setprio(0); } while (0)
; #define PG8_WAIT_V(n) asm volatile("s_waitcnt vmcnt(" #n ")" ::: "memory")
; #define PG8_WAIT_L(n) asm volatile("s_waitcnt lgkmcnt(" #n ")" ::: "memory")
; #define PG8_BAR __builtin_amdgcn_s_barrier()
; #define PG8_SCHED __builtin_amdgcn_sched_barrier(0)
; template <class Epi, class Sched, bool ALIGN_EPI = false, bool SP2 = false, bool AROWS128 = false>
; __device__ __forceinline__ void gemm_phase(PG8_LAS unsigned char* lds, const Gemm g, const Sched& S, const Epi& E) {
;     ...
;         for (int t = 0; t < nt; t += 2) {
;             const bool last = (t == nt - 2);
;             const char* a1 = cA + (size_t)(t + 1) * kstep;
;             const char* a2 = last ? nA : cA + (size_t)(t + 2) * kstep; const char* b2 = last ? nB : cB + (size_t)(t + 2) * kstep;
;     ...
;             PG8_LDA(At, 1, 1); PG8_STAGE(PG8_SB(1, 0), b3, voffB); PG8_STAGE(PG8_SB(1, 1), b3 + hstep, voffB); PG8_STAGE(PG8_SA(1, 0), a3, voffA);
;             PG8_WAIT_V(8); PG8_WAIT_L(0); PG8_BAR; PG8_MMA(1, 0, At, B0); PG8_MMA(1, 1, At, B1); PG8_BAR; PG8_SCHED;
	s_add_i32 s48, s78, s3
	v_lshl_add_u64 v[144:145], v[144:145], 0, s[8:9]
	s_mov_b32 m0, s48
	ds_read_b128 v[184:187], v151 offset:49152
	ds_read_b128 v[188:191], v151 offset:50176
	ds_read_b128 v[192:195], v151 offset:51200
	ds_read_b128 v[196:199], v151 offset:52224
	ds_read_b128 v[200:203], v151 offset:53248
	ds_read_b128 v[204:207], v151 offset:54272
	ds_read_b128 v[212:215], v151 offset:55296
	ds_read_b128 v[216:219], v151 offset:56320
	global_load_lds_dwordx4 v[144:145], off
	s_add_i32 m0, s48, 0x2000
	s_add_u32 s38, s38, 0x100080
	v_lshl_add_u64 v[144:145], v[208:209], 0, s[8:9]
	s_addc_u32 s39, s39, 0
	s_add_i32 s48, s79, s3
	global_load_lds_dwordx4 v[144:145], off
	v_lshl_add_u64 v[144:145], s[38:39], 0, v[132:133]
	s_mov_b32 m0, s48
	s_nop 0
	global_load_lds_dwordx4 v[144:145], off
	v_lshl_add_u64 v[144:145], s[38:39], 0, v[128:129]
	s_add_i32 m0, s48, 0x2000
	s_nop 0
	global_load_lds_dwordx4 v[144:145], off
	v_lshl_add_u64 v[144:145], v[220:221], 0, s[8:9]
	s_mov_b32 m0, s54
	s_nop 0
	global_load_lds_dwordx4 v[144:145], off
	v_lshl_add_u64 v[144:145], v[222:223], 0, s[8:9]
	s_mov_b32 m0, s55
	s_nop 0
	global_load_lds_dwordx4 v[144:145], off
	s_waitcnt vmcnt(8)
	s_waitcnt lgkmcnt(0)
	s_barrier
	s_setprio 1
	s_waitcnt lgkmcnt(0)
	v_mfma_f32_16x16x32_bf16 v[60:63], v[152:155], v[184:187], v[60:63]
	v_mfma_f32_16x16x32_bf16 v[56:59], v[160:163], v[184:187], v[56:59]
	v_mfma_f32_16x16x32_bf16 v[52:55], v[152:155], v[192:195], v[52:55]
	v_mfma_f32_16x16x32_bf16 v[44:47], v[160:163], v[192:195], v[44:47]
	v_mfma_f32_16x16x32_bf16 v[36:39], v[152:155], v[200:203], v[36:39]
	v_mfma_f32_16x16x32_bf16 v[28:31], v[160:163], v[200:203], v[28:31]
	v_mfma_f32_16x16x32_bf16 v[20:23], v[152:155], v[212:215], v[20:23]
	v_mfma_f32_16x16x32_bf16 v[12:15], v[160:163], v[212:215], v[12:15]
	v_mfma_f32_16x16x32_bf16 v[60:63], v[156:159], v[188:191], v[60:63]
	v_mfma_f32_16x16x32_bf16 v[56:59], v[164:167], v[188:191], v[56:59]
	v_mfma_f32_16x16x32_bf16 v[52:55], v[156:159], v[196:199], v[52:55]
	v_mfma_f32_16x16x32_bf16 v[44:47], v[164:167], v[196:199], v[44:47]
	v_mfma_f32_16x16x32_bf16 v[36:39], v[156:159], v[204:207], v[36:39]
	v_mfma_f32_16x16x32_bf16 v[28:31], v[164:167], v[204:207], v[28:31]
	v_mfma_f32_16x16x32_bf16 v[20:23], v[156:159], v[216:219], v[20:23]
	v_mfma_f32_16x16x32_bf16 v[12:15], v[164:167], v[216:219], v[12:15]
	s_setprio 0
	s_setprio 1
	v_mfma_f32_16x16x32_bf16 v[48:51], v[168:171], v[184:187], v[48:51]
	v_mfma_f32_16x16x32_bf16 v[40:43], v[176:179], v[184:187], v[40:43]
	v_mfma_f32_16x16x32_bf16 v[32:35], v[168:171], v[192:195], v[32:35]
	v_mfma_f32_16x16x32_bf16 v[24:27], v[176:179], v[192:195], v[24:27]
	v_mfma_f32_16x16x32_bf16 v[16:19], v[168:171], v[200:203], v[16:19]
	v_mfma_f32_16x16x32_bf16 v[8:11], v[176:179], v[200:203], v[8:11]
	v_mfma_f32_16x16x32_bf16 v[4:7], v[168:171], v[212:215], v[4:7]
	v_mfma_f32_16x16x32_bf16 v[0:3], v[176:179], v[212:215], v[0:3]
	v_mfma_f32_16x16x32_bf16 v[48:51], v[172:175], v[188:191], v[48:51]
	v_mfma_f32_16x16x32_bf16 v[40:43], v[180:183], v[188:191], v[40:43]
	v_mfma_f32_16x16x32_bf16 v[32:35], v[172:175], v[196:199], v[32:35]
	v_mfma_f32_16x16x32_bf16 v[24:27], v[180:183], v[196:199], v[24:27]
	v_mfma_f32_16x16x32_bf16 v[16:19], v[172:175], v[204:207], v[16:19]
	v_mfma_f32_16x16x32_bf16 v[8:11], v[180:183], v[204:207], v[8:11]
	v_mfma_f32_16x16x32_bf16 v[4:7], v[172:175], v[216:219], v[4:7]
	v_mfma_f32_16x16x32_bf16 v[0:3], v[180:183], v[216:219], v[0:3]
	s_setprio 0
	s_barrier
	s_add_i32 s77, s77, 2
	s_add_u32 s36, s36, 0x100
	s_addc_u32 s37, s37, 0
	s_add_u32 s73, s73, 0x100
	s_addc_u32 s76, s76, 0
	s_cmp_gt_u32 s77, 61
	s_cbranch_scc0 .LBB0_752
	s_and_b64 vcc, exec, s[10:11]
	s_cbranch_vccz .LBB0_755
	s_barrier

; #define PG8_STAGE(bufoff, gbase, voff) do { _Pragma("unroll") for (int _i = 0; _i < 2; ++_i) \
;         __builtin_amdgcn_global_load_lds((const unsigned*)((const char*)(gbase) + (voff)[_i]), (PG8_LAS unsigned*)(lds + (bufoff) + ldsw + _i * 8192), 16, 0, 0); } while (0)
; #define PG8_LDA(dst, b, h) do { _Pragma("unroll") for (int m = 0; m < 4; ++m) _Pragma("unroll") for (int k = 0; k < 2; ++k) dst[m][k] = *(const PG8_LAS bf16x8*)(lds + PG8_SA(b, h) + aoff + m * 2048 + k * 1024); } while (0)
; #define PG8_LDB(dst, b, h) do { _Pragma("unroll") for (int n = 0; n < 2; ++n) _Pragma("unroll") for (int k = 0; k < 2; ++k) dst[n][k] = *(const PG8_LAS bf16x8*)(lds + PG8_SB(b, h) + boff + n * 2048 + k * 1024); } while (0)
; #define PG8_MMA(ai, bj, At, Bt) do { __builtin_amdgcn_s_setprio(1); _Pragma("unroll") for (int m = 0; m < 4; ++m) _Pragma("unroll") for (int n = 0; n < 2; ++n) _Pragma("unroll") for (int k = 0; k < 2; ++k) \
;         acc[ai][bj][m][n] = __builtin_amdgcn_mfma_f32_16x16x32_bf16(Bt[n][k], At[m][k], acc[ai][bj][m][n], 0, 0, 0); __builtin_amdgcn_s_setprio(0); } while (0)
; #define PG8_WAIT_V(n) asm volatile("s_waitcnt vmcnt(" #n ")" ::: "memory")
; #define PG8_WAIT_L(n) asm volatile("s_waitcnt lgkmcnt(" #n ")" ::: "memory")
; template <class Epi, class Sched, bool ALIGN_EPI = false, bool SP2 = false, bool AROWS128 = false>
; __device__ __forceinline__ void gemm_phase(PG8_LAS unsigned char* lds, const Gemm g, const Sched& S, const Epi& E) {
;     ...
;             const bool last = (t == nt - 2);
;             const char* a1 = cA + (size_t)(t + 1) * kstep;
;             const char* a2 = last ? nA : cA + (size_t)(t + 2) * kstep; const char* b2 = last ? nB : cB + (size_t)(t + 2) * kstep;
;             const char* a3 = a2 + kstep; const char* b3 = b2 + kstep;
;             if (last && has_next) S.a_ready(nxt);
;             if constexpr (SP2) {
;             PG8_LDB(B0, 0, 0); PG8_LDB(B1, 0, 1); PG8_SCHED; PG8_LDA(At, 0, 0); PG8_STAGE(PG8_SA(1, 1), a1 + hstepA, voffA);
;             PG8_WAIT_V(8); PG8_WAIT_L(0); PG8_BAR; PG8_MMA(0, 0, At, B0); PG8_MMA(0, 1, At, B1); PG8_BAR; PG8_SCHED;
;             PG8_LDA(At, 0, 1); PG8_STAGE(PG8_SB(0, 0), b2, voffB); PG8_STAGE(PG8_SB(0, 1), b2 + hstep, voffB); PG8_STAGE(PG8_SA(0, 0), a2, voffA);
;             PG8_WAIT_V(8); PG8_WAIT_L(0); PG8_BAR; PG8_MMA(1, 0, At, B0); PG8_MMA(1, 1, At, B1); PG8_BAR; PG8_SCHED;
.LBB0_886:
	s_nop 0
	ds_read_b128 v[152:155], v149
	ds_read_b128 v[156:159], v149 offset:1024
	ds_read_b128 v[160:163], v149 offset:2048
	ds_read_b128 v[164:167], v149 offset:3072
	ds_read_b128 v[168:171], v150
	ds_read_b128 v[172:175], v150 offset:1024
	ds_read_b128 v[176:179], v150 offset:2048
	ds_read_b128 v[180:183], v150 offset:3072
	s_add_u32 s46, s42, 0xfffc0080
	s_addc_u32 s47, s43, -1
	s_cmp_eq_u32 s73, 12
	s_cselect_b32 s49, s31, s47
	s_cselect_b32 s48, s65, s46
	s_cselect_b32 s47, s29, s72
	s_cselect_b32 s46, s66, s67
	v_lshl_add_u64 v[144:145], s[42:43], 0, v[136:137]
	s_add_i32 m0, s41, 0xc000
	ds_read_b128 v[184:187], v151
	ds_read_b128 v[188:191], v151 offset:1024
	ds_read_b128 v[192:195], v151 offset:2048
	ds_read_b128 v[196:199], v151 offset:3072
	ds_read_b128 v[200:203], v151 offset:4096
	ds_read_b128 v[204:207], v151 offset:5120
	ds_read_b128 v[212:215], v151 offset:6144
	ds_read_b128 v[216:219], v151 offset:7168
	global_load_lds_dwordx4 v[144:145], off
	v_lshl_add_u64 v[144:145], s[42:43], 0, v[138:139]
	s_add_i32 m0, s41, 0xe000
	s_nop 0
	global_load_lds_dwordx4 v[144:145], off
	s_waitcnt vmcnt(8)
	s_waitcnt lgkmcnt(0)
	s_barrier
	s_setprio 1
	s_waitcnt lgkmcnt(0)
	v_mfma_f32_16x16x32_bf16 v[124:127], v[152:155], v[184:187], v[124:127]
	v_mfma_f32_16x16x32_bf16 v[120:123], v[160:163], v[184:187], v[120:123]
	v_mfma_f32_16x16x32_bf16 v[116:119], v[152:155], v[192:195], v[116:119]
	v_mfma_f32_16x16x32_bf16 v[108:111], v[160:163], v[192:195], v[108:111]
	v_mfma_f32_16x16x32_bf16 v[100:103], v[152:155], v[200:203], v[100:103]
	v_mfma_f32_16x16x32_bf16 v[92:95], v[160:163], v[200:203], v[92:95]
	v_mfma_f32_16x16x32_bf16 v[84:87], v[152:155], v[212:215], v[84:87]
	v_mfma_f32_16x16x32_bf16 v[76:79], v[160:163], v[212:215], v[76:79]
	v_mfma_f32_16x16x32_bf16 v[124:127], v[156:159], v[188:191], v[124:127]
	v_mfma_f32_16x16x32_bf16 v[120:123], v[164:167], v[188:191], v[120:123]
	v_mfma_f32_16x16x32_bf16 v[116:119], v[156:159], v[196:199], v[116:119]
	v_mfma_f32_16x16x32_bf16 v[108:111], v[164:167], v[196:199], v[108:111]
	v_mfma_f32_16x16x32_bf16 v[100:103], v[156:159], v[204:207], v[100:103]
	v_mfma_f32_16x16x32_bf16 v[92:95], v[164:167], v[204:207], v[92:95]
	v_mfma_f32_16x16x32_bf16 v[84:87], v[156:159], v[216:219], v[84:87]
	v_mfma_f32_16x16x32_bf16 v[76:79], v[164:167], v[216:219], v[76:79]
	s_setprio 0
	s_setprio 1
	v_mfma_f32_16x16x32_bf16 v[112:115], v[168:171], v[184:187], v[112:115]
	v_mfma_f32_16x16x32_bf16 v[104:107], v[176:179], v[184:187], v[104:107]
	v_mfma_f32_16x16x32_bf16 v[96:99], v[168:171], v[192:195], v[96:99]
	v_mfma_f32_16x16x32_bf16 v[88:91], v[176:179], v[192:195], v[88:91]
	v_mfma_f32_16x16x32_bf16 v[80:83], v[168:171], v[200:203], v[80:83]
	v_mfma_f32_16x16x32_bf16 v[72:75], v[176:179], v[200:203], v[72:75]
	v_mfma_f32_16x16x32_bf16 v[68:71], v[168:171], v[212:215], v[68:71]
	v_mfma_f32_16x16x32_bf16 v[64:67], v[176:179], v[212:215], v[64:67]
	v_mfma_f32_16x16x32_bf16 v[112:115], v[172:175], v[188:191], v[112:115]
	v_mfma_f32_16x16x32_bf16 v[104:107], v[180:183], v[188:191], v[104:107]
	v_mfma_f32_16x16x32_bf16 v[96:99], v[172:175], v[196:199], v[96:99]
	v_mfma_f32_16x16x32_bf16 v[88:91], v[180:183], v[196:199], v[88:91]
	v_mfma_f32_16x16x32_bf16 v[80:83], v[172:175], v[204:207], v[80:83]
	v_mfma_f32_16x16x32_bf16 v[72:75], v[180:183], v[204:207], v[72:75]
	v_mfma_f32_16x16x32_bf16 v[68:71], v[172:175], v[216:219], v[68:71]
	v_mfma_f32_16x16x32_bf16 v[64:67], v[180:183], v[216:219], v[64:67]
	s_setprio 0
	s_barrier
	s_nop 0
	s_add_i32 s76, s58, s3
	v_lshl_add_u64 v[144:145], s[46:47], 0, v[132:133]
	s_mov_b32 m0, s76
	ds_read_b128 v[184:187], v151 offset:16384
	ds_read_b128 v[188:191], v151 offset:17408
	ds_read_b128 v[192:195], v151 offset:18432
	ds_read_b128 v[196:199], v151 offset:19456
	ds_read_b128 v[200:203], v151 offset:20480
	ds_read_b128 v[204:207], v151 offset:21504
	ds_read_b128 v[212:215], v151 offset:22528
	ds_read_b128 v[216:219], v151 offset:23552
	global_load_lds_dwordx4 v[144:145], off
	s_add_i32 m0, s76, 0x2000
	s_add_u32 s76, s46, 0x40000
	v_lshl_add_u64 v[208:209], s[46:47], 0, v[128:129]
	s_addc_u32 s77, s47, 0
	s_add_i32 s78, s59, s3
	global_load_lds_dwordx4 v[208:209], off
	v_lshl_add_u64 v[220:221], s[76:77], 0, v[132:133]
	s_mov_b32 m0, s78
	v_lshl_add_u64 v[222:223], s[48:49], 0, v[130:131]
	global_load_lds_dwordx4 v[220:221], off
	v_lshl_add_u64 v[220:221], s[76:77], 0, v[128:129]
	s_add_i32 m0, s78, 0x2000
	s_nop 0
	global_load_lds_dwordx4 v[220:221], off
	v_lshl_add_u64 v[220:221], s[48:49], 0, v[134:135]
	s_mov_b32 m0, s41
	s_nop 0
	global_load_lds_dwordx4 v[220:221], off
	s_mov_b32 m0, s50
	s_nop 0
	global_load_lds_dwordx4 v[222:223], off
	s_waitcnt vmcnt(8)
	s_waitcnt lgkmcnt(0)
	s_barrier
; #define PG8_STAGE(bufoff, gbase, voff) do { _Pragma("unroll") for (int _i = 0; _i < 2; ++_i) \
;         __builtin_amdgcn_global_load_lds((const unsigned*)((const char*)(gbase) + (voff)[_i]), (PG8_LAS unsigned*)(lds + (bufoff) + ldsw + _i * 8192), 16, 0, 0); } while (0)
; #define PG8_LDA(dst, b, h) do { _Pragma("unroll") for (int m = 0; m < 4; ++m) _Pragma("unroll") for (int k = 0; k < 2; ++k) dst[m][k] = *(const PG8_LAS bf16x8*)(lds + PG8_SA(b, h) + aoff + m * 2048 + k * 1024); } while (0)
; #define PG8_LDB(dst, b, h) do { _Pragma("unroll") for (int n = 0; n < 2; ++n) _Pragma("unroll") for (int k = 0; k < 2; ++k) dst[n][k] = *(const PG8_LAS bf16x8*)(lds + PG8_SB(b, h) + boff + n * 2048 + k * 1024); } while (0)
; #define PG8_MMA(ai, bj, At, Bt) do { __builtin_amdgcn_s_setprio(1); _Pragma("unroll") for (int m = 0; m < 4; ++m) _Pragma("unroll") for (int n = 0; n < 2; ++n) _Pragma("unroll") for (int k = 0; k < 2; ++k) \
;         acc[ai][bj][m][n] = __builtin_amdgcn_mfma_f32_16x16x32_bf16(Bt[n][k], At[m][k], acc[ai][bj][m][n], 0, 0, 0); __builtin_amdgcn_s_setprio(0); } while (0)
; #define PG8_WAIT_V(n) asm volatile("s_waitcnt vmcnt(" #n ")" ::: "memory")
; #define PG8_WAIT_L(n) asm volatile("s_waitcnt lgkmcnt(" #n ")" ::: "memory")
; #define PG8_BAR __builtin_amdgcn_s_barrier()
; #define PG8_SCHED __builtin_amdgcn_sched_barrier(0)
; template <class Epi, class Sched, bool ALIGN_EPI = false, bool SP2 = false, bool AROWS128 = false>
; __device__ __forceinline__ void gemm_phase(PG8_LAS unsigned char* lds, const Gemm g, const Sched& S, const Epi& E) {
;     ...
;             PG8_WAIT_V(8); PG8_WAIT_L(0); PG8_BAR; PG8_MMA(1, 0, At, B0); PG8_MMA(1, 1, At, B1); PG8_BAR; PG8_SCHED;
;             PG8_LDB(B0, 1, 0); PG8_LDB(B1, 1, 1); PG8_SCHED; PG8_LDA(At, 1, 0); PG8_STAGE(PG8_SA(0, 1), a2 + hstepA, voffA);
;             PG8_WAIT_V(8); PG8_WAIT_L(0); PG8_BAR; PG8_MMA(0, 0, At, B0); PG8_MMA(0, 1, At, B1); PG8_BAR; PG8_SCHED;
	s_setprio 1
	s_waitcnt lgkmcnt(0)
	v_mfma_f32_16x16x32_bf16 v[60:63], v[152:155], v[184:187], v[60:63]
	v_mfma_f32_16x16x32_bf16 v[56:59], v[160:163], v[184:187], v[56:59]
	v_mfma_f32_16x16x32_bf16 v[52:55], v[152:155], v[192:195], v[52:55]
	v_mfma_f32_16x16x32_bf16 v[44:47], v[160:163], v[192:195], v[44:47]
	v_mfma_f32_16x16x32_bf16 v[36:39], v[152:155], v[200:203], v[36:39]
	v_mfma_f32_16x16x32_bf16 v[28:31], v[160:163], v[200:203], v[28:31]
	v_mfma_f32_16x16x32_bf16 v[20:23], v[152:155], v[212:215], v[20:23]
	v_mfma_f32_16x16x32_bf16 v[12:15], v[160:163], v[212:215], v[12:15]
	v_mfma_f32_16x16x32_bf16 v[60:63], v[156:159], v[188:191], v[60:63]
	v_mfma_f32_16x16x32_bf16 v[56:59], v[164:167], v[188:191], v[56:59]
	v_mfma_f32_16x16x32_bf16 v[52:55], v[156:159], v[196:199], v[52:55]
	v_mfma_f32_16x16x32_bf16 v[44:47], v[164:167], v[196:199], v[44:47]
	v_mfma_f32_16x16x32_bf16 v[36:39], v[156:159], v[204:207], v[36:39]
	v_mfma_f32_16x16x32_bf16 v[28:31], v[164:167], v[204:207], v[28:31]
	v_mfma_f32_16x16x32_bf16 v[20:23], v[156:159], v[216:219], v[20:23]
	v_mfma_f32_16x16x32_bf16 v[12:15], v[164:167], v[216:219], v[12:15]
	s_setprio 0
	s_setprio 1
	v_mfma_f32_16x16x32_bf16 v[48:51], v[168:171], v[184:187], v[48:51]
	v_mfma_f32_16x16x32_bf16 v[40:43], v[176:179], v[184:187], v[40:43]
	v_mfma_f32_16x16x32_bf16 v[32:35], v[168:171], v[192:195], v[32:35]
	v_mfma_f32_16x16x32_bf16 v[24:27], v[176:179], v[192:195], v[24:27]
	v_mfma_f32_16x16x32_bf16 v[16:19], v[168:171], v[200:203], v[16:19]
	v_mfma_f32_16x16x32_bf16 v[8:11], v[176:179], v[200:203], v[8:11]
	v_mfma_f32_16x16x32_bf16 v[4:7], v[168:171], v[212:215], v[4:7]
	v_mfma_f32_16x16x32_bf16 v[0:3], v[176:179], v[212:215], v[0:3]
	v_mfma_f32_16x16x32_bf16 v[48:51], v[172:175], v[188:191], v[48:51]
	v_mfma_f32_16x16x32_bf16 v[40:43], v[180:183], v[188:191], v[40:43]
	v_mfma_f32_16x16x32_bf16 v[32:35], v[172:175], v[196:199], v[32:35]
	v_mfma_f32_16x16x32_bf16 v[24:27], v[180:183], v[196:199], v[24:27]
	v_mfma_f32_16x16x32_bf16 v[16:19], v[172:175], v[204:207], v[16:19]
	v_mfma_f32_16x16x32_bf16 v[8:11], v[180:183], v[204:207], v[8:11]
	v_mfma_f32_16x16x32_bf16 v[4:7], v[172:175], v[216:219], v[4:7]
	v_mfma_f32_16x16x32_bf16 v[0:3], v[180:183], v[216:219], v[0:3]
	s_setprio 0
	s_barrier
	s_nop 0
	s_add_i32 s76, 0, 0x18000
	s_add_i32 s77, 0, 0x1c000
	v_add_u32_e32 v164, s76, v147
	v_add_u32_e32 v180, s77, v147
	ds_read_b128 v[152:155], v164
	ds_read_b128 v[156:159], v164 offset:1024
	ds_read_b128 v[160:163], v164 offset:2048
	ds_read_b128 v[164:167], v164 offset:3072
	ds_read_b128 v[168:171], v180
	ds_read_b128 v[172:175], v180 offset:1024
	ds_read_b128 v[176:179], v180 offset:2048
	ds_read_b128 v[180:183], v180 offset:3072
	s_add_u32 s48, s48, 0x40000
	s_addc_u32 s49, s49, 0
	s_mov_b32 m0, s51
	v_lshl_add_u64 v[224:225], s[48:49], 0, v[134:135]
	ds_read_b128 v[184:187], v151 offset:32768
	ds_read_b128 v[188:191], v151 offset:33792
	ds_read_b128 v[192:195], v151 offset:34816
	ds_read_b128 v[196:199], v151 offset:35840
	ds_read_b128 v[200:203], v151 offset:36864
	ds_read_b128 v[204:207], v151 offset:37888
	ds_read_b128 v[212:215], v151 offset:38912
	ds_read_b128 v[216:219], v151 offset:39936
	global_load_lds_dwordx4 v[224:225], off
	v_lshl_add_u64 v[224:225], s[48:49], 0, v[130:131]
	s_mov_b32 m0, s52
	s_nop 0
	global_load_lds_dwordx4 v[224:225], off
	s_waitcnt vmcnt(8)
	s_waitcnt lgkmcnt(0)
	s_barrier
	s_setprio 1
	s_waitcnt lgkmcnt(0)
	v_mfma_f32_16x16x32_bf16 v[124:127], v[152:155], v[184:187], v[124:127]
	v_mfma_f32_16x16x32_bf16 v[120:123], v[160:163], v[184:187], v[120:123]
	v_mfma_f32_16x16x32_bf16 v[116:119], v[152:155], v[192:195], v[116:119]
	v_mfma_f32_16x16x32_bf16 v[108:111], v[160:163], v[192:195], v[108:111]
	v_mfma_f32_16x16x32_bf16 v[100:103], v[152:155], v[200:203], v[100:103]
	v_mfma_f32_16x16x32_bf16 v[92:95], v[160:163], v[200:203], v[92:95]
	v_mfma_f32_16x16x32_bf16 v[84:87], v[152:155], v[212:215], v[84:87]
	v_mfma_f32_16x16x32_bf16 v[76:79], v[160:163], v[212:215], v[76:79]
	v_mfma_f32_16x16x32_bf16 v[124:127], v[156:159], v[188:191], v[124:127]
	v_mfma_f32_16x16x32_bf16 v[120:123], v[164:167], v[188:191], v[120:123]
	v_mfma_f32_16x16x32_bf16 v[116:119], v[156:159], v[196:199], v[116:119]
	v_mfma_f32_16x16x32_bf16 v[108:111], v[164:167], v[196:199], v[108:111]
	v_mfma_f32_16x16x32_bf16 v[100:103], v[156:159], v[204:207], v[100:103]
	v_mfma_f32_16x16x32_bf16 v[92:95], v[164:167], v[204:207], v[92:95]
	v_mfma_f32_16x16x32_bf16 v[84:87], v[156:159], v[216:219], v[84:87]
	v_mfma_f32_16x16x32_bf16 v[76:79], v[164:167], v[216:219], v[76:79]
	s_setprio 0
	s_setprio 1
	v_mfma_f32_16x16x32_bf16 v[112:115], v[168:171], v[184:187], v[112:115]
	v_mfma_f32_16x16x32_bf16 v[104:107], v[176:179], v[184:187], v[104:107]
	v_mfma_f32_16x16x32_bf16 v[96:99], v[168:171], v[192:195], v[96:99]
	v_mfma_f32_16x16x32_bf16 v[88:91], v[176:179], v[192:195], v[88:91]
	v_mfma_f32_16x16x32_bf16 v[80:83], v[168:171], v[200:203], v[80:83]
	v_mfma_f32_16x16x32_bf16 v[72:75], v[176:179], v[200:203], v[72:75]
	v_mfma_f32_16x16x32_bf16 v[68:71], v[168:171], v[212:215], v[68:71]
	v_mfma_f32_16x16x32_bf16 v[64:67], v[176:179], v[212:215], v[64:67]
	v_mfma_f32_16x16x32_bf16 v[112:115], v[172:175], v[188:191], v[112:115]
	v_mfma_f32_16x16x32_bf16 v[104:107], v[180:183], v[188:191], v[104:107]
	v_mfma_f32_16x16x32_bf16 v[96:99], v[172:175], v[196:199], v[96:99]
	v_mfma_f32_16x16x32_bf16 v[88:91], v[180:183], v[196:199], v[88:91]
	v_mfma_f32_16x16x32_bf16 v[80:83], v[172:175], v[204:207], v[80:83]
	v_mfma_f32_16x16x32_bf16 v[72:75], v[180:183], v[204:207], v[72:75]
	v_mfma_f32_16x16x32_bf16 v[68:71], v[172:175], v[216:219], v[68:71]
	v_mfma_f32_16x16x32_bf16 v[64:67], v[180:183], v[216:219], v[64:67]
	s_setprio 0
	s_barrier
; #define PG8_STAGE(bufoff, gbase, voff) do { _Pragma("unroll") for (int _i = 0; _i < 2; ++_i) \
;         __builtin_amdgcn_global_load_lds((const unsigned*)((const char*)(gbase) + (voff)[_i]), (PG8_LAS unsigned*)(lds + (bufoff) + ldsw + _i * 8192), 16, 0, 0); } while (0)
; #define PG8_LDA(dst, b, h) do { _Pragma("unroll") for (int m = 0; m < 4; ++m) _Pragma("unroll") for (int k = 0; k < 2; ++k) dst[m][k] = *(const PG8_LAS bf16x8*)(lds + PG8_SA(b, h) + aoff + m * 2048 + k * 1024); } while (0)
; #define PG8_MMA(ai, bj, At, Bt) do { __builtin_amdgcn_s_setprio(1); _Pragma("unroll") for (int m = 0; m < 4; ++m) _Pragma("unroll") for (int n = 0; n < 2; ++n) _Pragma("unroll") for (int k = 0; k < 2; ++k) \
;         acc[ai][bj][m][n] = __builtin_amdgcn_mfma_f32_16x16x32_bf16(Bt[n][k], At[m][k], acc[ai][bj][m][n], 0, 0, 0); __builtin_amdgcn_s_setprio(0); } while (0)
; #define PG8_WAIT_V(n) asm volatile("s_waitcnt vmcnt(" #n ")" ::: "memory")
; #define PG8_WAIT_L(n) asm volatile("s_waitcnt lgkmcnt(" #n ")" ::: "memory")
; #define PG8_BAR __builtin_amdgcn_s_barrier()
; #define PG8_SCHED __builtin_amdgcn_sched_barrier(0)
; template <class Epi, class Sched, bool ALIGN_EPI = false, bool SP2 = false, bool AROWS128 = false>
; __device__ __forceinline__ void gemm_phase(PG8_LAS unsigned char* lds, const Gemm g, const Sched& S, const Epi& E) {
;     ...
;         for (int t = 0; t < nt; t += 2) {
;             const bool last = (t == nt - 2);
;             const char* a1 = cA + (size_t)(t + 1) * kstep;
;             const char* a2 = last ? nA : cA + (size_t)(t + 2) * kstep; const char* b2 = last ? nB : cB + (size_t)(t + 2) * kstep;
;     ...
;             PG8_LDA(At, 1, 1); PG8_STAGE(PG8_SB(1, 0), b3, voffB); PG8_STAGE(PG8_SB(1, 1), b3 + hstep, voffB); PG8_STAGE(PG8_SA(1, 0), a3, voffA);
;             PG8_WAIT_V(8); PG8_WAIT_L(0); PG8_BAR; PG8_MMA(1, 0, At, B0); PG8_MMA(1, 1, At, B1); PG8_BAR; PG8_SCHED;
	s_add_i32 s48, s76, s3
	v_lshl_add_u64 v[144:145], v[144:145], 0, s[16:17]
	s_mov_b32 m0, s48
	ds_read_b128 v[184:187], v151 offset:49152
	ds_read_b128 v[188:191], v151 offset:50176
	ds_read_b128 v[192:195], v151 offset:51200
	ds_read_b128 v[196:199], v151 offset:52224
	ds_read_b128 v[200:203], v151 offset:53248
	ds_read_b128 v[204:207], v151 offset:54272
	ds_read_b128 v[212:215], v151 offset:55296
	ds_read_b128 v[216:219], v151 offset:56320
	global_load_lds_dwordx4 v[144:145], off
	s_add_i32 m0, s48, 0x2000
	s_add_u32 s46, s46, 0x40080
	v_lshl_add_u64 v[144:145], v[208:209], 0, s[16:17]
	s_addc_u32 s47, s47, 0
	s_add_i32 s48, s77, s3
	global_load_lds_dwordx4 v[144:145], off
	v_lshl_add_u64 v[144:145], s[46:47], 0, v[132:133]
	s_mov_b32 m0, s48
	s_nop 0
	global_load_lds_dwordx4 v[144:145], off
	v_lshl_add_u64 v[144:145], s[46:47], 0, v[128:129]
	s_add_i32 m0, s48, 0x2000
	s_nop 0
	global_load_lds_dwordx4 v[144:145], off
	v_lshl_add_u64 v[144:145], v[220:221], 0, s[16:17]
	s_mov_b32 m0, s54
	s_nop 0
	global_load_lds_dwordx4 v[144:145], off
	v_lshl_add_u64 v[144:145], v[222:223], 0, s[16:17]
	s_mov_b32 m0, s55
	s_nop 0
	global_load_lds_dwordx4 v[144:145], off
	s_waitcnt vmcnt(8)
	s_waitcnt lgkmcnt(0)
	s_barrier
	s_setprio 1
	s_waitcnt lgkmcnt(0)
	v_mfma_f32_16x16x32_bf16 v[60:63], v[152:155], v[184:187], v[60:63]
	v_mfma_f32_16x16x32_bf16 v[56:59], v[160:163], v[184:187], v[56:59]
	v_mfma_f32_16x16x32_bf16 v[52:55], v[152:155], v[192:195], v[52:55]
	v_mfma_f32_16x16x32_bf16 v[44:47], v[160:163], v[192:195], v[44:47]
	v_mfma_f32_16x16x32_bf16 v[36:39], v[152:155], v[200:203], v[36:39]
	v_mfma_f32_16x16x32_bf16 v[28:31], v[160:163], v[200:203], v[28:31]
	v_mfma_f32_16x16x32_bf16 v[20:23], v[152:155], v[212:215], v[20:23]
	v_mfma_f32_16x16x32_bf16 v[12:15], v[160:163], v[212:215], v[12:15]
	v_mfma_f32_16x16x32_bf16 v[60:63], v[156:159], v[188:191], v[60:63]
	v_mfma_f32_16x16x32_bf16 v[56:59], v[164:167], v[188:191], v[56:59]
	v_mfma_f32_16x16x32_bf16 v[52:55], v[156:159], v[196:199], v[52:55]
	v_mfma_f32_16x16x32_bf16 v[44:47], v[164:167], v[196:199], v[44:47]
	v_mfma_f32_16x16x32_bf16 v[36:39], v[156:159], v[204:207], v[36:39]
	v_mfma_f32_16x16x32_bf16 v[28:31], v[164:167], v[204:207], v[28:31]
	v_mfma_f32_16x16x32_bf16 v[20:23], v[156:159], v[216:219], v[20:23]
	v_mfma_f32_16x16x32_bf16 v[12:15], v[164:167], v[216:219], v[12:15]
	s_setprio 0
	s_setprio 1
	v_mfma_f32_16x16x32_bf16 v[48:51], v[168:171], v[184:187], v[48:51]
	v_mfma_f32_16x16x32_bf16 v[40:43], v[176:179], v[184:187], v[40:43]
	v_mfma_f32_16x16x32_bf16 v[32:35], v[168:171], v[192:195], v[32:35]
	v_mfma_f32_16x16x32_bf16 v[24:27], v[176:179], v[192:195], v[24:27]
	v_mfma_f32_16x16x32_bf16 v[16:19], v[168:171], v[200:203], v[16:19]
	v_mfma_f32_16x16x32_bf16 v[8:11], v[176:179], v[200:203], v[8:11]
	v_mfma_f32_16x16x32_bf16 v[4:7], v[168:171], v[212:215], v[4:7]
	v_mfma_f32_16x16x32_bf16 v[0:3], v[176:179], v[212:215], v[0:3]
	v_mfma_f32_16x16x32_bf16 v[48:51], v[172:175], v[188:191], v[48:51]
	v_mfma_f32_16x16x32_bf16 v[40:43], v[180:183], v[188:191], v[40:43]
	v_mfma_f32_16x16x32_bf16 v[32:35], v[172:175], v[196:199], v[32:35]
	v_mfma_f32_16x16x32_bf16 v[24:27], v[180:183], v[196:199], v[24:27]
	v_mfma_f32_16x16x32_bf16 v[16:19], v[172:175], v[204:207], v[16:19]
	v_mfma_f32_16x16x32_bf16 v[8:11], v[180:183], v[204:207], v[8:11]
	v_mfma_f32_16x16x32_bf16 v[4:7], v[172:175], v[216:219], v[4:7]
	v_mfma_f32_16x16x32_bf16 v[0:3], v[180:183], v[216:219], v[0:3]
	s_setprio 0
	s_barrier
	s_add_i32 s73, s73, 2
	s_add_u32 s42, s42, 0x100
	s_addc_u32 s43, s43, 0
	s_add_u32 s67, s67, 0x100
	s_addc_u32 s72, s72, 0
	s_cmp_gt_u32 s73, 13
	s_cbranch_scc0 .LBB0_886
	s_and_b64 vcc, exec, s[18:19]
	s_cbranch_vccz .LBB0_889
	s_barrier
